# hand-written specialised weight-conversion queues, software-pipelined across iterations (both conv tails); on top of v34
# baseline (speedup 1.0000x reference)
; template <int NT> __device__ __forceinline__ void conv_tilesN(const Params& p, LAS unsigned char* lds, int tid, int t0, int stride, int t_end) {
;   unsigned char* ws = p.ws;
;   LAS float* tile = (LAS float*)lds;
;   const int tx = tid & 63, ty = tid >> 6;
;   {
;     float v[NT][8];
; #pragma unroll
;     for (int q = 0; q < NT; ++q) {
;       const int t = t0 + q * stride;
;       if (t < t_end) {
;         int mat, loc, ktn;
;         if (t < 7680) { mat = 0; loc = t; ktn = 32; }
;         else if (t < 9728) { mat = 1; loc = t - 7680; ktn = 64; }
;         else if (t < 10752) { mat = 2; loc = t - 9728; ktn = 32; }
;         else if (t < 16384) { mat = 3; loc = t - 10752; ktn = 32; }
;         else if (t < 19200) { mat = 4; loc = t - 16384; ktn = 88; }
;         else { mat = 5; loc = t - 19200; ktn = 32; }
;         const int n0 = (loc / ktn) * 64, k0 = (loc % ktn) * 64;
;         const int n = n0 + tx;
;         const float* ptr; int ld, col, kk0 = k0;
;         if (mat == 0) {
;           ptr = p.in[6]; ld = INW; col = n;
;           if (n >= OFF_RQ && n < OFF_RV) { const int s = n & 127; col = (n & ~127) + ((s >> 4) & 1) * 64 + (s >> 5) * 16 + (s & 15); }
;         } else if (mat == 1) {
;           ld = 2048; col = n;
;           if (k0 < 1024) { ptr = p.in[11]; } else if (k0 < 3072) { ptr = p.in[13]; kk0 = k0 - 1024; } else { ptr = p.in[16]; kk0 = k0 - 3072; }
;         } else if (mat == 2) { ptr = p.in[17]; ld = 2048; col = n; }
;         else if (mat == 3) {
;           const int T = n >> 8, s = n & 255;
;           const int f = 128 * T + 64 * (s >> 7) + 16 * ((s >> 5) & 3) + (s & 15);
;           ptr = ((s >> 4) & 1) ? p.in[21] : p.in[20]; ld = DFF; col = f;
;         } else if (mat == 4) { ptr = p.in[22]; ld = 2048; col = n; }
; __device__ __forceinline__ void conv_queue(const Params& p, LAS unsigned char* lds, unsigned* ctr, int t_begin, int t_end) {
;   int tid = threadIdx.x; asm volatile("" : "+v"(tid));
;   LAS unsigned* slot = (LAS unsigned*)(lds + LDS_CTL);
;   unsigned nxt = 0u;
;   if (tid == 0) nxt = atomicAdd(ctr, 4u);
;   for (;;) {
;     __syncthreads();
;     if (tid == 0) *slot = nxt;
;     __syncthreads();
;     const int base = t_begin + (int)__builtin_amdgcn_readfirstlane(*slot);
;     if (base >= t_end) break;
;     if (tid == 0) nxt = atomicAdd(ctr, 4u);
;     conv_tilesN<4>(p, lds, tid, base, 1, t_end);
.LBB0_994:
	s_cmp_eq_u32 s74, 3
	v_readlane_b32 s72, v255, 33
	s_cselect_b64 s[38:39], -1, 0
	s_cmp_lg_u32 s74, 3
	v_readlane_b32 s73, v255, 34
	s_movk_i32 s71, 0xc7
	s_mov_b32 s74, 0x40000
	s_cbranch_scc1 .LBB0_1198
	s_branch .Lcvb_entry
.Lcvb_entry:
	v_and_b32_e32 v0, 63, v226
	v_lshrrev_b32_e32 v2, 6, v226
	v_lshlrev_b32_e32 v2, 3, v2
	v_lshrrev_b32_e32 v3, 3, v226
	v_and_b32_e32 v4, 7, v226
	v_lshlrev_b32_e32 v4, 3, v4
	v_mul_u32_u24_e32 v5, 0x41, v2
	v_add_u32_e32 v5, v5, v0
	v_lshlrev_b32_e32 v5, 2, v5
	v_mul_u32_u24_e32 v6, 0x41, v4
	v_add_u32_e32 v6, v6, v3
	v_lshlrev_b32_e32 v6, 2, v6
	v_lshlrev_b32_e32 v4, 1, v4
	v_lshrrev_b32_e32 v1, 5, v0
	v_lshlrev_b32_e32 v1, 4, v1
	v_and_b32_e32 v7, 15, v0
	v_or_b32_e32 v1, v1, v7
	v_lshlrev_b32_e32 v1, 2, v1
	v_and_b32_e32 v7, 16, v0
	v_lshlrev_b32_e32 v0, 2, v0
	v_mov_b32_e32 v8, 0x25ff0
	v_mov_b32_e32 v9, 4
	v_mov_b32_e32 v10, 0
	v_cmp_eq_u32_e64 s[44:45], 0, v226
	s_mov_b32 s53, 0
	s_and_saveexec_b64 s[40:41], s[44:45]
	s_cbranch_execz .Lcvb_f0_a
	global_atomic_add v10, v65, v9, s[24:25] offset:20 sc0
.Lcvb_f0_a:
	s_mov_b64 exec, s[40:41]
	s_waitcnt vmcnt(0) lgkmcnt(0)
	s_barrier
	s_and_saveexec_b64 s[40:41], s[44:45]
	s_cbranch_execz .Lcvb_x0_w
	ds_write_b32 v8, v10
.Lcvb_x0_w:
	s_mov_b64 exec, s[40:41]
	s_waitcnt lgkmcnt(0)
	s_barrier
	ds_read_b32 v11, v8
	s_waitcnt lgkmcnt(0)
	s_nop 0
	v_readfirstlane_b32 s46, v11
	s_nop 1
	s_add_i32 s46, s46, 0x4000
	s_cmp_ge_i32 s46, 0x4b00
	s_cbranch_scc1 .Lcvb_done
	s_and_saveexec_b64 s[40:41], s[44:45]
	s_cbranch_execz .Lcvb_f1_a
	global_atomic_add v10, v65, v9, s[24:25] offset:20 sc0
.Lcvb_f1_a:
	s_mov_b64 exec, s[40:41]
	s_add_i32 s47, s46, 0
	s_sub_i32 s54, s47, 0x4000
	s_mul_i32 s55, s54, 0xba3
	s_lshr_b32 s55, s55, 18
	s_mul_i32 s59, s55, 88
	s_sub_i32 s54, s54, s59
	s_lshl_b32 s54, s54, 6
	s_lshl_b32 s55, s55, 6
	s_mov_b32 s52, 0x2000
	v_readlane_b32 s48, v251, 28
	v_readlane_b32 s49, v251, 29
	s_mov_b32 s60, s54
	s_mul_i32 s60, s60, 0x2000
	s_lshl_b32 s61, s55, 2
	s_add_i32 s60, s60, s61
	s_add_u32 s48, s48, s60
	s_addc_u32 s49, s49, 0
	v_mad_u32_u24 v12, v2, s52, v0
	v_mov_b32_e32 v13, 0
	v_lshl_add_u64 v[12:13], s[48:49], 0, v[12:13]
.Lcvb_p_l0_dd:
	global_load_dword v16, v[12:13], off nt
	v_lshl_add_u64 v[12:13], v[12:13], 0, s[52:53]
	global_load_dword v17, v[12:13], off nt
	v_lshl_add_u64 v[12:13], v[12:13], 0, s[52:53]
	global_load_dword v18, v[12:13], off nt
	v_lshl_add_u64 v[12:13], v[12:13], 0, s[52:53]
	global_load_dword v19, v[12:13], off nt
	v_lshl_add_u64 v[12:13], v[12:13], 0, s[52:53]
	global_load_dword v20, v[12:13], off nt
	v_lshl_add_u64 v[12:13], v[12:13], 0, s[52:53]
	global_load_dword v21, v[12:13], off nt
	v_lshl_add_u64 v[12:13], v[12:13], 0, s[52:53]
	global_load_dword v22, v[12:13], off nt
	v_lshl_add_u64 v[12:13], v[12:13], 0, s[52:53]
	global_load_dword v23, v[12:13], off nt
	s_add_i32 s47, s46, 1
	s_sub_i32 s54, s47, 0x4000
	s_mul_i32 s55, s54, 0xba3
	s_lshr_b32 s55, s55, 18
	s_mul_i32 s59, s55, 88
	s_sub_i32 s54, s54, s59
	s_lshl_b32 s54, s54, 6
	s_lshl_b32 s55, s55, 6
	s_mov_b32 s52, 0x2000
	v_readlane_b32 s48, v251, 28
	v_readlane_b32 s49, v251, 29
	s_mov_b32 s60, s54
	s_mul_i32 s60, s60, 0x2000
	s_lshl_b32 s61, s55, 2
	s_add_i32 s60, s60, s61
	s_add_u32 s48, s48, s60
	s_addc_u32 s49, s49, 0
	v_mad_u32_u24 v12, v2, s52, v0
	v_mov_b32_e32 v13, 0
	v_lshl_add_u64 v[12:13], s[48:49], 0, v[12:13]
.Lcvb_p_l1_dd:
	global_load_dword v24, v[12:13], off nt
	v_lshl_add_u64 v[12:13], v[12:13], 0, s[52:53]
	global_load_dword v25, v[12:13], off nt
	v_lshl_add_u64 v[12:13], v[12:13], 0, s[52:53]
	global_load_dword v26, v[12:13], off nt
	v_lshl_add_u64 v[12:13], v[12:13], 0, s[52:53]
	global_load_dword v27, v[12:13], off nt
	v_lshl_add_u64 v[12:13], v[12:13], 0, s[52:53]
	global_load_dword v28, v[12:13], off nt
	v_lshl_add_u64 v[12:13], v[12:13], 0, s[52:53]
	global_load_dword v29, v[12:13], off nt
	v_lshl_add_u64 v[12:13], v[12:13], 0, s[52:53]
	global_load_dword v30, v[12:13], off nt
	v_lshl_add_u64 v[12:13], v[12:13], 0, s[52:53]
	global_load_dword v31, v[12:13], off nt
	s_add_i32 s47, s46, 2
	s_sub_i32 s54, s47, 0x4000
	s_mul_i32 s55, s54, 0xba3
	s_lshr_b32 s55, s55, 18
	s_mul_i32 s59, s55, 88
	s_sub_i32 s54, s54, s59
	s_lshl_b32 s54, s54, 6
	s_lshl_b32 s55, s55, 6
	s_mov_b32 s52, 0x2000
	v_readlane_b32 s48, v251, 28
	v_readlane_b32 s49, v251, 29
	s_mov_b32 s60, s54
	s_mul_i32 s60, s60, 0x2000
	s_lshl_b32 s61, s55, 2
	s_add_i32 s60, s60, s61
	s_add_u32 s48, s48, s60
	s_addc_u32 s49, s49, 0
	v_mad_u32_u24 v12, v2, s52, v0
	v_mov_b32_e32 v13, 0
	v_lshl_add_u64 v[12:13], s[48:49], 0, v[12:13]
.Lcvb_p_l2_dd:
	global_load_dword v32, v[12:13], off nt
	v_lshl_add_u64 v[12:13], v[12:13], 0, s[52:53]
	global_load_dword v33, v[12:13], off nt
	v_lshl_add_u64 v[12:13], v[12:13], 0, s[52:53]
	global_load_dword v34, v[12:13], off nt
	v_lshl_add_u64 v[12:13], v[12:13], 0, s[52:53]
	global_load_dword v35, v[12:13], off nt
	v_lshl_add_u64 v[12:13], v[12:13], 0, s[52:53]
	global_load_dword v36, v[12:13], off nt
	v_lshl_add_u64 v[12:13], v[12:13], 0, s[52:53]
	global_load_dword v37, v[12:13], off nt
	v_lshl_add_u64 v[12:13], v[12:13], 0, s[52:53]
	global_load_dword v38, v[12:13], off nt
	v_lshl_add_u64 v[12:13], v[12:13], 0, s[52:53]
	global_load_dword v39, v[12:13], off nt
	s_add_i32 s47, s46, 3
	s_sub_i32 s54, s47, 0x4000
	s_mul_i32 s55, s54, 0xba3
	s_lshr_b32 s55, s55, 18
	s_mul_i32 s59, s55, 88
	s_sub_i32 s54, s54, s59
	s_lshl_b32 s54, s54, 6
	s_lshl_b32 s55, s55, 6
	s_mov_b32 s52, 0x2000
	v_readlane_b32 s48, v251, 28
	v_readlane_b32 s49, v251, 29
	s_mov_b32 s60, s54
	s_mul_i32 s60, s60, 0x2000
	s_lshl_b32 s61, s55, 2
	s_add_i32 s60, s60, s61
	s_add_u32 s48, s48, s60
	s_addc_u32 s49, s49, 0
	v_mad_u32_u24 v12, v2, s52, v0
	v_mov_b32_e32 v13, 0
	v_lshl_add_u64 v[12:13], s[48:49], 0, v[12:13]
; __device__ __forceinline__ unsigned cvt_pk(float lo, float hi) { const f32x2 v = {lo, hi}; const bf16x2_t b = __builtin_convertvector(v, bf16x2_t); return __builtin_bit_cast(unsigned, b); }
; template <int NT> __device__ __forceinline__ void conv_tilesN(const Params& p, LAS unsigned char* lds, int tid, int t0, int stride, int t_end) {
;     ...
;         const float* s0 = ptr + (size_t)(kk0 + ty * 8) * ld + col;
; #pragma unroll
;         for (int r = 0; r < 8; ++r) v[q][r] = __builtin_nontemporal_load(s0 + (size_t)r * ld);
;       }
;     }
; #pragma unroll
;     for (int q = 0; q < NT; ++q) {
;       const int t = t0 + q * stride;
;       if (t < t_end) {
;         int loc, ktn, ldd; size_t dsto;
;         if (t < 7680) { loc = t; ktn = 32; ldd = 2048; dsto = WS_WIN; }
;         else if (t < 9728) { loc = t - 7680; ktn = 64; ldd = 4096; dsto = WS_WCAT; }
;         else if (t < 10752) { loc = t - 9728; ktn = 32; ldd = 2048; dsto = WS_WOUT; }
;         else if (t < 16384) { loc = t - 10752; ktn = 32; ldd = 2048; dsto = WS_WGU; }
;         else if (t < 19200) { loc = t - 16384; ktn = 88; ldd = 5632; dsto = WS_WDN; }
;         else { loc = t - 19200; ktn = 32; ldd = 2048; dsto = WS_WMKV; }
;         const int n0 = (loc / ktn) * 64, k0 = (loc % ktn) * 64;
;         __syncthreads();
; #pragma unroll
;         for (int r = 0; r < 8; ++r) tile[(ty * 8 + r) * 65 + tx] = v[q][r];
;         __syncthreads();
;         const int nn = tid >> 3, kc = (tid & 7) * 8;
;         float w[8];
; #pragma unroll
;         for (int e = 0; e < 8; ++e) w[e] = tile[(kc + e) * 65 + nn];
;         u32x4 o; o[0] = cvt_pk(w[0], w[1]); o[1] = cvt_pk(w[2], w[3]); o[2] = cvt_pk(w[4], w[5]); o[3] = cvt_pk(w[6], w[7]);
;         *(u32x4*)((bf16_t*)(ws + dsto) + (size_t)(n0 + nn) * ldd + k0 + kc) = o;
; __device__ __forceinline__ void conv_queue(const Params& p, LAS unsigned char* lds, unsigned* ctr, int t_begin, int t_end) {
;     ...
;   for (;;) {
;     __syncthreads();
;     if (tid == 0) *slot = nxt;
;     __syncthreads();
;     const int base = t_begin + (int)__builtin_amdgcn_readfirstlane(*slot);
;     if (base >= t_end) break;
;     if (tid == 0) nxt = atomicAdd(ctr, 4u);
;     conv_tilesN<4>(p, lds, tid, base, 1, t_end);
.Lcvb_p_l3_dd:
	global_load_dword v40, v[12:13], off nt
	v_lshl_add_u64 v[12:13], v[12:13], 0, s[52:53]
	global_load_dword v41, v[12:13], off nt
	v_lshl_add_u64 v[12:13], v[12:13], 0, s[52:53]
	global_load_dword v42, v[12:13], off nt
	v_lshl_add_u64 v[12:13], v[12:13], 0, s[52:53]
	global_load_dword v43, v[12:13], off nt
	v_lshl_add_u64 v[12:13], v[12:13], 0, s[52:53]
	global_load_dword v44, v[12:13], off nt
	v_lshl_add_u64 v[12:13], v[12:13], 0, s[52:53]
	global_load_dword v45, v[12:13], off nt
	v_lshl_add_u64 v[12:13], v[12:13], 0, s[52:53]
	global_load_dword v46, v[12:13], off nt
	v_lshl_add_u64 v[12:13], v[12:13], 0, s[52:53]
	global_load_dword v47, v[12:13], off nt
.Lcvb_v0_top:
	s_waitcnt vmcnt(32) lgkmcnt(0)
	s_barrier
	s_and_saveexec_b64 s[40:41], s[44:45]
	s_cbranch_execz .Lcvb_v0x_w
	ds_write_b32 v8, v10
.Lcvb_v0x_w:
	s_mov_b64 exec, s[40:41]
	s_waitcnt lgkmcnt(0)
	s_barrier
	ds_read_b32 v11, v8
	s_waitcnt lgkmcnt(0)
	s_nop 0
	v_readfirstlane_b32 s63, v11
	s_nop 1
	s_add_i32 s63, s63, 0x4000
	s_and_saveexec_b64 s[40:41], s[44:45]
	s_cbranch_execz .Lcvb_v0f_a
	global_atomic_add v10, v65, v9, s[24:25] offset:20 sc0
.Lcvb_v0f_a:
	s_mov_b64 exec, s[40:41]
	s_add_i32 s47, s46, 0
	s_sub_i32 s54, s47, 0x4000
	s_mul_i32 s55, s54, 0xba3
	s_lshr_b32 s55, s55, 18
	s_mul_i32 s59, s55, 88
	s_sub_i32 s54, s54, s59
	s_lshl_b32 s54, s54, 6
	s_lshl_b32 s55, s55, 6
	s_mov_b32 s58, 0x2c00
	s_mul_i32 s60, s55, 0x2c00
	s_lshl_b32 s61, s54, 1
	s_add_i32 s60, s60, s61
	s_add_u32 s56, s24, 0xa509000
	s_addc_u32 s57, s25, 0
	s_add_u32 s56, s56, s60
	s_addc_u32 s57, s57, 0
	v_mad_u32_u24 v14, v3, s58, v4
.Lcvb_v0_t_s0_dd:
	s_waitcnt vmcnt(24)
	ds_write_b32 v5, v16
	ds_write_b32 v5, v17 offset:260
	ds_write_b32 v5, v18 offset:520
	ds_write_b32 v5, v19 offset:780
	ds_write_b32 v5, v20 offset:1040
	ds_write_b32 v5, v21 offset:1300
	ds_write_b32 v5, v22 offset:1560
	ds_write_b32 v5, v23 offset:1820
	s_waitcnt lgkmcnt(0)
	s_barrier
	ds_read_b32 v48, v6
	ds_read_b32 v49, v6 offset:260
	ds_read_b32 v50, v6 offset:520
	ds_read_b32 v51, v6 offset:780
	ds_read_b32 v52, v6 offset:1040
	ds_read_b32 v53, v6 offset:1300
	ds_read_b32 v54, v6 offset:1560
	ds_read_b32 v55, v6 offset:1820
	s_waitcnt lgkmcnt(0)
	v_cvt_pk_bf16_f32 v56, v48, v49
	v_cvt_pk_bf16_f32 v57, v50, v51
	v_cvt_pk_bf16_f32 v58, v52, v53
	v_cvt_pk_bf16_f32 v59, v54, v55
	global_store_dwordx4 v14, v[56:59], s[56:57]
	s_cmp_ge_i32 s63, 0x4b00
	s_cbranch_scc1 .Lcvb_v0_last
	s_add_i32 s47, s63, 0
	s_sub_i32 s54, s47, 0x4000
	s_mul_i32 s55, s54, 0xba3
	s_lshr_b32 s55, s55, 18
	s_mul_i32 s59, s55, 88
	s_sub_i32 s54, s54, s59
	s_lshl_b32 s54, s54, 6
	s_lshl_b32 s55, s55, 6
	s_mov_b32 s52, 0x2000
	v_readlane_b32 s48, v251, 28
	v_readlane_b32 s49, v251, 29
	s_mov_b32 s60, s54
	s_mul_i32 s60, s60, 0x2000
	s_lshl_b32 s61, s55, 2
	s_add_i32 s60, s60, s61
	s_add_u32 s48, s48, s60
	s_addc_u32 s49, s49, 0
	v_mad_u32_u24 v12, v2, s52, v0
	v_mov_b32_e32 v13, 0
	v_lshl_add_u64 v[12:13], s[48:49], 0, v[12:13]
.Lcvb_v0_n_l0_dd:
	global_load_dword v68, v[12:13], off nt
	v_lshl_add_u64 v[12:13], v[12:13], 0, s[52:53]
	global_load_dword v69, v[12:13], off nt
	v_lshl_add_u64 v[12:13], v[12:13], 0, s[52:53]
	global_load_dword v70, v[12:13], off nt
	v_lshl_add_u64 v[12:13], v[12:13], 0, s[52:53]
	global_load_dword v71, v[12:13], off nt
	v_lshl_add_u64 v[12:13], v[12:13], 0, s[52:53]
	global_load_dword v72, v[12:13], off nt
	v_lshl_add_u64 v[12:13], v[12:13], 0, s[52:53]
	global_load_dword v73, v[12:13], off nt
	v_lshl_add_u64 v[12:13], v[12:13], 0, s[52:53]
	global_load_dword v74, v[12:13], off nt
	v_lshl_add_u64 v[12:13], v[12:13], 0, s[52:53]
	global_load_dword v75, v[12:13], off nt
	s_add_i32 s47, s63, 1
	s_sub_i32 s54, s47, 0x4000
	s_mul_i32 s55, s54, 0xba3
	s_lshr_b32 s55, s55, 18
	s_mul_i32 s59, s55, 88
	s_sub_i32 s54, s54, s59
	s_lshl_b32 s54, s54, 6
	s_lshl_b32 s55, s55, 6
	s_mov_b32 s52, 0x2000
	v_readlane_b32 s48, v251, 28
	v_readlane_b32 s49, v251, 29
	s_mov_b32 s60, s54
	s_mul_i32 s60, s60, 0x2000
	s_lshl_b32 s61, s55, 2
	s_add_i32 s60, s60, s61
	s_add_u32 s48, s48, s60
	s_addc_u32 s49, s49, 0
	v_mad_u32_u24 v12, v2, s52, v0
	v_mov_b32_e32 v13, 0
	v_lshl_add_u64 v[12:13], s[48:49], 0, v[12:13]
.Lcvb_v0_n_l1_dd:
	global_load_dword v76, v[12:13], off nt
	v_lshl_add_u64 v[12:13], v[12:13], 0, s[52:53]
	global_load_dword v77, v[12:13], off nt
	v_lshl_add_u64 v[12:13], v[12:13], 0, s[52:53]
	global_load_dword v78, v[12:13], off nt
	v_lshl_add_u64 v[12:13], v[12:13], 0, s[52:53]
	global_load_dword v79, v[12:13], off nt
	v_lshl_add_u64 v[12:13], v[12:13], 0, s[52:53]
	global_load_dword v80, v[12:13], off nt
	v_lshl_add_u64 v[12:13], v[12:13], 0, s[52:53]
	global_load_dword v81, v[12:13], off nt
	v_lshl_add_u64 v[12:13], v[12:13], 0, s[52:53]
	global_load_dword v82, v[12:13], off nt
	v_lshl_add_u64 v[12:13], v[12:13], 0, s[52:53]
	global_load_dword v83, v[12:13], off nt
	s_add_i32 s47, s63, 2
	s_sub_i32 s54, s47, 0x4000
	s_mul_i32 s55, s54, 0xba3
	s_lshr_b32 s55, s55, 18
	s_mul_i32 s59, s55, 88
	s_sub_i32 s54, s54, s59
	s_lshl_b32 s54, s54, 6
	s_lshl_b32 s55, s55, 6
	s_mov_b32 s52, 0x2000
	v_readlane_b32 s48, v251, 28
	v_readlane_b32 s49, v251, 29
	s_mov_b32 s60, s54
	s_mul_i32 s60, s60, 0x2000
	s_lshl_b32 s61, s55, 2
	s_add_i32 s60, s60, s61
	s_add_u32 s48, s48, s60
	s_addc_u32 s49, s49, 0
	v_mad_u32_u24 v12, v2, s52, v0
	v_mov_b32_e32 v13, 0
	v_lshl_add_u64 v[12:13], s[48:49], 0, v[12:13]
; __device__ __forceinline__ unsigned cvt_pk(float lo, float hi) { const f32x2 v = {lo, hi}; const bf16x2_t b = __builtin_convertvector(v, bf16x2_t); return __builtin_bit_cast(unsigned, b); }
; template <int NT> __device__ __forceinline__ void conv_tilesN(const Params& p, LAS unsigned char* lds, int tid, int t0, int stride, int t_end) {
;     ...
;         const float* s0 = ptr + (size_t)(kk0 + ty * 8) * ld + col;
; #pragma unroll
;         for (int r = 0; r < 8; ++r) v[q][r] = __builtin_nontemporal_load(s0 + (size_t)r * ld);
;       }
;     }
; #pragma unroll
;     for (int q = 0; q < NT; ++q) {
;       const int t = t0 + q * stride;
;       if (t < t_end) {
;         int loc, ktn, ldd; size_t dsto;
;         if (t < 7680) { loc = t; ktn = 32; ldd = 2048; dsto = WS_WIN; }
;         else if (t < 9728) { loc = t - 7680; ktn = 64; ldd = 4096; dsto = WS_WCAT; }
;         else if (t < 10752) { loc = t - 9728; ktn = 32; ldd = 2048; dsto = WS_WOUT; }
;         else if (t < 16384) { loc = t - 10752; ktn = 32; ldd = 2048; dsto = WS_WGU; }
;         else if (t < 19200) { loc = t - 16384; ktn = 88; ldd = 5632; dsto = WS_WDN; }
;         else { loc = t - 19200; ktn = 32; ldd = 2048; dsto = WS_WMKV; }
;         const int n0 = (loc / ktn) * 64, k0 = (loc % ktn) * 64;
;         __syncthreads();
; #pragma unroll
;         for (int r = 0; r < 8; ++r) tile[(ty * 8 + r) * 65 + tx] = v[q][r];
;         __syncthreads();
;         const int nn = tid >> 3, kc = (tid & 7) * 8;
;         float w[8];
; #pragma unroll
;         for (int e = 0; e < 8; ++e) w[e] = tile[(kc + e) * 65 + nn];
;         u32x4 o; o[0] = cvt_pk(w[0], w[1]); o[1] = cvt_pk(w[2], w[3]); o[2] = cvt_pk(w[4], w[5]); o[3] = cvt_pk(w[6], w[7]);
;         *(u32x4*)((bf16_t*)(ws + dsto) + (size_t)(n0 + nn) * ldd + k0 + kc) = o;
.Lcvb_v0_n_l2_dd:
	global_load_dword v84, v[12:13], off nt
	v_lshl_add_u64 v[12:13], v[12:13], 0, s[52:53]
	global_load_dword v85, v[12:13], off nt
	v_lshl_add_u64 v[12:13], v[12:13], 0, s[52:53]
	global_load_dword v86, v[12:13], off nt
	v_lshl_add_u64 v[12:13], v[12:13], 0, s[52:53]
	global_load_dword v87, v[12:13], off nt
	v_lshl_add_u64 v[12:13], v[12:13], 0, s[52:53]
	global_load_dword v88, v[12:13], off nt
	v_lshl_add_u64 v[12:13], v[12:13], 0, s[52:53]
	global_load_dword v89, v[12:13], off nt
	v_lshl_add_u64 v[12:13], v[12:13], 0, s[52:53]
	global_load_dword v90, v[12:13], off nt
	v_lshl_add_u64 v[12:13], v[12:13], 0, s[52:53]
	global_load_dword v91, v[12:13], off nt
	s_add_i32 s47, s63, 3
	s_sub_i32 s54, s47, 0x4000
	s_mul_i32 s55, s54, 0xba3
	s_lshr_b32 s55, s55, 18
	s_mul_i32 s59, s55, 88
	s_sub_i32 s54, s54, s59
	s_lshl_b32 s54, s54, 6
	s_lshl_b32 s55, s55, 6
	s_mov_b32 s52, 0x2000
	v_readlane_b32 s48, v251, 28
	v_readlane_b32 s49, v251, 29
	s_mov_b32 s60, s54
	s_mul_i32 s60, s60, 0x2000
	s_lshl_b32 s61, s55, 2
	s_add_i32 s60, s60, s61
	s_add_u32 s48, s48, s60
	s_addc_u32 s49, s49, 0
	v_mad_u32_u24 v12, v2, s52, v0
	v_mov_b32_e32 v13, 0
	v_lshl_add_u64 v[12:13], s[48:49], 0, v[12:13]
.Lcvb_v0_n_l3_dd:
	global_load_dword v92, v[12:13], off nt
	v_lshl_add_u64 v[12:13], v[12:13], 0, s[52:53]
	global_load_dword v93, v[12:13], off nt
	v_lshl_add_u64 v[12:13], v[12:13], 0, s[52:53]
	global_load_dword v94, v[12:13], off nt
	v_lshl_add_u64 v[12:13], v[12:13], 0, s[52:53]
	global_load_dword v95, v[12:13], off nt
	v_lshl_add_u64 v[12:13], v[12:13], 0, s[52:53]
	global_load_dword v96, v[12:13], off nt
	v_lshl_add_u64 v[12:13], v[12:13], 0, s[52:53]
	global_load_dword v97, v[12:13], off nt
	v_lshl_add_u64 v[12:13], v[12:13], 0, s[52:53]
	global_load_dword v98, v[12:13], off nt
	v_lshl_add_u64 v[12:13], v[12:13], 0, s[52:53]
	global_load_dword v99, v[12:13], off nt
	s_add_i32 s47, s46, 1
	s_sub_i32 s54, s47, 0x4000
	s_mul_i32 s55, s54, 0xba3
	s_lshr_b32 s55, s55, 18
	s_mul_i32 s59, s55, 88
	s_sub_i32 s54, s54, s59
	s_lshl_b32 s54, s54, 6
	s_lshl_b32 s55, s55, 6
	s_mov_b32 s58, 0x2c00
	s_mul_i32 s60, s55, 0x2c00
	s_lshl_b32 s61, s54, 1
	s_add_i32 s60, s60, s61
	s_add_u32 s56, s24, 0xa509000
	s_addc_u32 s57, s25, 0
	s_add_u32 s56, s56, s60
	s_addc_u32 s57, s57, 0
	v_mad_u32_u24 v14, v3, s58, v4
.Lcvb_v0_a_s1_dd:
	s_barrier
	s_waitcnt vmcnt(48)
	ds_write_b32 v5, v24
	ds_write_b32 v5, v25 offset:260
	ds_write_b32 v5, v26 offset:520
	ds_write_b32 v5, v27 offset:780
	ds_write_b32 v5, v28 offset:1040
	ds_write_b32 v5, v29 offset:1300
	ds_write_b32 v5, v30 offset:1560
	ds_write_b32 v5, v31 offset:1820
	s_waitcnt lgkmcnt(0)
	s_barrier
	ds_read_b32 v48, v6
	ds_read_b32 v49, v6 offset:260
	ds_read_b32 v50, v6 offset:520
	ds_read_b32 v51, v6 offset:780
	ds_read_b32 v52, v6 offset:1040
	ds_read_b32 v53, v6 offset:1300
	ds_read_b32 v54, v6 offset:1560
	ds_read_b32 v55, v6 offset:1820
	s_waitcnt lgkmcnt(0)
	v_cvt_pk_bf16_f32 v56, v48, v49
	v_cvt_pk_bf16_f32 v57, v50, v51
	v_cvt_pk_bf16_f32 v58, v52, v53
	v_cvt_pk_bf16_f32 v59, v54, v55
	global_store_dwordx4 v14, v[56:59], s[56:57]
	s_add_i32 s47, s46, 2
	s_sub_i32 s54, s47, 0x4000
	s_mul_i32 s55, s54, 0xba3
	s_lshr_b32 s55, s55, 18
	s_mul_i32 s59, s55, 88
	s_sub_i32 s54, s54, s59
	s_lshl_b32 s54, s54, 6
	s_lshl_b32 s55, s55, 6
	s_mov_b32 s58, 0x2c00
	s_mul_i32 s60, s55, 0x2c00
	s_lshl_b32 s61, s54, 1
	s_add_i32 s60, s60, s61
	s_add_u32 s56, s24, 0xa509000
	s_addc_u32 s57, s25, 0
	s_add_u32 s56, s56, s60
	s_addc_u32 s57, s57, 0
	v_mad_u32_u24 v14, v3, s58, v4
.Lcvb_v0_a_s2_dd:
	s_barrier
	s_waitcnt vmcnt(40)
	ds_write_b32 v5, v32
	ds_write_b32 v5, v33 offset:260
	ds_write_b32 v5, v34 offset:520
	ds_write_b32 v5, v35 offset:780
	ds_write_b32 v5, v36 offset:1040
	ds_write_b32 v5, v37 offset:1300
	ds_write_b32 v5, v38 offset:1560
	ds_write_b32 v5, v39 offset:1820
	s_waitcnt lgkmcnt(0)
	s_barrier
	ds_read_b32 v48, v6
	ds_read_b32 v49, v6 offset:260
	ds_read_b32 v50, v6 offset:520
	ds_read_b32 v51, v6 offset:780
	ds_read_b32 v52, v6 offset:1040
	ds_read_b32 v53, v6 offset:1300
	ds_read_b32 v54, v6 offset:1560
	ds_read_b32 v55, v6 offset:1820
	s_waitcnt lgkmcnt(0)
	v_cvt_pk_bf16_f32 v56, v48, v49
	v_cvt_pk_bf16_f32 v57, v50, v51
	v_cvt_pk_bf16_f32 v58, v52, v53
	v_cvt_pk_bf16_f32 v59, v54, v55
	global_store_dwordx4 v14, v[56:59], s[56:57]
	s_add_i32 s47, s46, 3
	s_sub_i32 s54, s47, 0x4000
	s_mul_i32 s55, s54, 0xba3
	s_lshr_b32 s55, s55, 18
	s_mul_i32 s59, s55, 88
	s_sub_i32 s54, s54, s59
	s_lshl_b32 s54, s54, 6
	s_lshl_b32 s55, s55, 6
	s_mov_b32 s58, 0x2c00
	s_mul_i32 s60, s55, 0x2c00
	s_lshl_b32 s61, s54, 1
	s_add_i32 s60, s60, s61
	s_add_u32 s56, s24, 0xa509000
	s_addc_u32 s57, s25, 0
	s_add_u32 s56, s56, s60
	s_addc_u32 s57, s57, 0
	v_mad_u32_u24 v14, v3, s58, v4
; __device__ __forceinline__ unsigned cvt_pk(float lo, float hi) { const f32x2 v = {lo, hi}; const bf16x2_t b = __builtin_convertvector(v, bf16x2_t); return __builtin_bit_cast(unsigned, b); }
; template <int NT> __device__ __forceinline__ void conv_tilesN(const Params& p, LAS unsigned char* lds, int tid, int t0, int stride, int t_end) {
;     ...
;     for (int q = 0; q < NT; ++q) {
;       const int t = t0 + q * stride;
;       if (t < t_end) {
;         int loc, ktn, ldd; size_t dsto;
;         if (t < 7680) { loc = t; ktn = 32; ldd = 2048; dsto = WS_WIN; }
;         else if (t < 9728) { loc = t - 7680; ktn = 64; ldd = 4096; dsto = WS_WCAT; }
;         else if (t < 10752) { loc = t - 9728; ktn = 32; ldd = 2048; dsto = WS_WOUT; }
;         else if (t < 16384) { loc = t - 10752; ktn = 32; ldd = 2048; dsto = WS_WGU; }
;         else if (t < 19200) { loc = t - 16384; ktn = 88; ldd = 5632; dsto = WS_WDN; }
;         else { loc = t - 19200; ktn = 32; ldd = 2048; dsto = WS_WMKV; }
;         const int n0 = (loc / ktn) * 64, k0 = (loc % ktn) * 64;
;         __syncthreads();
; #pragma unroll
;         for (int r = 0; r < 8; ++r) tile[(ty * 8 + r) * 65 + tx] = v[q][r];
;         __syncthreads();
;         const int nn = tid >> 3, kc = (tid & 7) * 8;
;         float w[8];
; #pragma unroll
;         for (int e = 0; e < 8; ++e) w[e] = tile[(kc + e) * 65 + nn];
;         u32x4 o; o[0] = cvt_pk(w[0], w[1]); o[1] = cvt_pk(w[2], w[3]); o[2] = cvt_pk(w[4], w[5]); o[3] = cvt_pk(w[6], w[7]);
;         *(u32x4*)((bf16_t*)(ws + dsto) + (size_t)(n0 + nn) * ldd + k0 + kc) = o;
.Lcvb_v0_a_s3_dd:
	s_barrier
	s_waitcnt vmcnt(32)
	ds_write_b32 v5, v40
	ds_write_b32 v5, v41 offset:260
	ds_write_b32 v5, v42 offset:520
	ds_write_b32 v5, v43 offset:780
	ds_write_b32 v5, v44 offset:1040
	ds_write_b32 v5, v45 offset:1300
	ds_write_b32 v5, v46 offset:1560
	ds_write_b32 v5, v47 offset:1820
	s_waitcnt lgkmcnt(0)
	s_barrier
	ds_read_b32 v48, v6
	ds_read_b32 v49, v6 offset:260
	ds_read_b32 v50, v6 offset:520
	ds_read_b32 v51, v6 offset:780
	ds_read_b32 v52, v6 offset:1040
	ds_read_b32 v53, v6 offset:1300
	ds_read_b32 v54, v6 offset:1560
	ds_read_b32 v55, v6 offset:1820
	s_waitcnt lgkmcnt(0)
	v_cvt_pk_bf16_f32 v56, v48, v49
	v_cvt_pk_bf16_f32 v57, v50, v51
	v_cvt_pk_bf16_f32 v58, v52, v53
	v_cvt_pk_bf16_f32 v59, v54, v55
	global_store_dwordx4 v14, v[56:59], s[56:57]
	s_mov_b32 s46, s63
	s_branch .Lcvb_v1_top
.Lcvb_v0_last:
	s_add_i32 s47, s46, 1
	s_sub_i32 s54, s47, 0x4000
	s_mul_i32 s55, s54, 0xba3
	s_lshr_b32 s55, s55, 18
	s_mul_i32 s59, s55, 88
	s_sub_i32 s54, s54, s59
	s_lshl_b32 s54, s54, 6
	s_lshl_b32 s55, s55, 6
	s_mov_b32 s58, 0x2c00
	s_mul_i32 s60, s55, 0x2c00
	s_lshl_b32 s61, s54, 1
	s_add_i32 s60, s60, s61
	s_add_u32 s56, s24, 0xa509000
	s_addc_u32 s57, s25, 0
	s_add_u32 s56, s56, s60
	s_addc_u32 s57, s57, 0
	v_mad_u32_u24 v14, v3, s58, v4
.Lcvb_v0_b_s1_dd:
	s_barrier
	s_waitcnt vmcnt(16)
	ds_write_b32 v5, v24
	ds_write_b32 v5, v25 offset:260
	ds_write_b32 v5, v26 offset:520
	ds_write_b32 v5, v27 offset:780
	ds_write_b32 v5, v28 offset:1040
	ds_write_b32 v5, v29 offset:1300
	ds_write_b32 v5, v30 offset:1560
	ds_write_b32 v5, v31 offset:1820
	s_waitcnt lgkmcnt(0)
	s_barrier
	ds_read_b32 v48, v6
	ds_read_b32 v49, v6 offset:260
	ds_read_b32 v50, v6 offset:520
	ds_read_b32 v51, v6 offset:780
	ds_read_b32 v52, v6 offset:1040
	ds_read_b32 v53, v6 offset:1300
	ds_read_b32 v54, v6 offset:1560
	ds_read_b32 v55, v6 offset:1820
	s_waitcnt lgkmcnt(0)
	v_cvt_pk_bf16_f32 v56, v48, v49
	v_cvt_pk_bf16_f32 v57, v50, v51
	v_cvt_pk_bf16_f32 v58, v52, v53
	v_cvt_pk_bf16_f32 v59, v54, v55
	global_store_dwordx4 v14, v[56:59], s[56:57]
	s_add_i32 s47, s46, 2
	s_sub_i32 s54, s47, 0x4000
	s_mul_i32 s55, s54, 0xba3
	s_lshr_b32 s55, s55, 18
	s_mul_i32 s59, s55, 88
	s_sub_i32 s54, s54, s59
	s_lshl_b32 s54, s54, 6
	s_lshl_b32 s55, s55, 6
	s_mov_b32 s58, 0x2c00
	s_mul_i32 s60, s55, 0x2c00
	s_lshl_b32 s61, s54, 1
	s_add_i32 s60, s60, s61
	s_add_u32 s56, s24, 0xa509000
	s_addc_u32 s57, s25, 0
	s_add_u32 s56, s56, s60
	s_addc_u32 s57, s57, 0
	v_mad_u32_u24 v14, v3, s58, v4
.Lcvb_v0_b_s2_dd:
	s_barrier
	s_waitcnt vmcnt(8)
	ds_write_b32 v5, v32
	ds_write_b32 v5, v33 offset:260
	ds_write_b32 v5, v34 offset:520
	ds_write_b32 v5, v35 offset:780
	ds_write_b32 v5, v36 offset:1040
	ds_write_b32 v5, v37 offset:1300
	ds_write_b32 v5, v38 offset:1560
	ds_write_b32 v5, v39 offset:1820
	s_waitcnt lgkmcnt(0)
	s_barrier
	ds_read_b32 v48, v6
	ds_read_b32 v49, v6 offset:260
	ds_read_b32 v50, v6 offset:520
	ds_read_b32 v51, v6 offset:780
	ds_read_b32 v52, v6 offset:1040
	ds_read_b32 v53, v6 offset:1300
	ds_read_b32 v54, v6 offset:1560
	ds_read_b32 v55, v6 offset:1820
	s_waitcnt lgkmcnt(0)
	v_cvt_pk_bf16_f32 v56, v48, v49
	v_cvt_pk_bf16_f32 v57, v50, v51
	v_cvt_pk_bf16_f32 v58, v52, v53
	v_cvt_pk_bf16_f32 v59, v54, v55
	global_store_dwordx4 v14, v[56:59], s[56:57]
	s_add_i32 s47, s46, 3
	s_sub_i32 s54, s47, 0x4000
	s_mul_i32 s55, s54, 0xba3
	s_lshr_b32 s55, s55, 18
	s_mul_i32 s59, s55, 88
	s_sub_i32 s54, s54, s59
	s_lshl_b32 s54, s54, 6
	s_lshl_b32 s55, s55, 6
	s_mov_b32 s58, 0x2c00
	s_mul_i32 s60, s55, 0x2c00
	s_lshl_b32 s61, s54, 1
	s_add_i32 s60, s60, s61
	s_add_u32 s56, s24, 0xa509000
	s_addc_u32 s57, s25, 0
	s_add_u32 s56, s56, s60
	s_addc_u32 s57, s57, 0
	v_mad_u32_u24 v14, v3, s58, v4
.Lcvb_v0_b_s3_dd:
	s_barrier
	s_waitcnt vmcnt(0)
	ds_write_b32 v5, v40
	ds_write_b32 v5, v41 offset:260
	ds_write_b32 v5, v42 offset:520
	ds_write_b32 v5, v43 offset:780
	ds_write_b32 v5, v44 offset:1040
	ds_write_b32 v5, v45 offset:1300
	ds_write_b32 v5, v46 offset:1560
	ds_write_b32 v5, v47 offset:1820
	s_waitcnt lgkmcnt(0)
	s_barrier
	ds_read_b32 v48, v6
	ds_read_b32 v49, v6 offset:260
	ds_read_b32 v50, v6 offset:520
	ds_read_b32 v51, v6 offset:780
	ds_read_b32 v52, v6 offset:1040
	ds_read_b32 v53, v6 offset:1300
	ds_read_b32 v54, v6 offset:1560
	ds_read_b32 v55, v6 offset:1820
	s_waitcnt lgkmcnt(0)
	v_cvt_pk_bf16_f32 v56, v48, v49
	v_cvt_pk_bf16_f32 v57, v50, v51
	v_cvt_pk_bf16_f32 v58, v52, v53
	v_cvt_pk_bf16_f32 v59, v54, v55
	global_store_dwordx4 v14, v[56:59], s[56:57]
	s_branch .Lcvb_done

; __device__ __forceinline__ unsigned cvt_pk(float lo, float hi) { const f32x2 v = {lo, hi}; const bf16x2_t b = __builtin_convertvector(v, bf16x2_t); return __builtin_bit_cast(unsigned, b); }
; template <int NT> __device__ __forceinline__ void conv_tilesN(const Params& p, LAS unsigned char* lds, int tid, int t0, int stride, int t_end) {
;     ...
;         const float* s0 = ptr + (size_t)(kk0 + ty * 8) * ld + col;
; #pragma unroll
;         for (int r = 0; r < 8; ++r) v[q][r] = __builtin_nontemporal_load(s0 + (size_t)r * ld);
;       }
;     }
; #pragma unroll
;     for (int q = 0; q < NT; ++q) {
;       const int t = t0 + q * stride;
;       if (t < t_end) {
;         int loc, ktn, ldd; size_t dsto;
;         if (t < 7680) { loc = t; ktn = 32; ldd = 2048; dsto = WS_WIN; }
;         else if (t < 9728) { loc = t - 7680; ktn = 64; ldd = 4096; dsto = WS_WCAT; }
;         else if (t < 10752) { loc = t - 9728; ktn = 32; ldd = 2048; dsto = WS_WOUT; }
;         else if (t < 16384) { loc = t - 10752; ktn = 32; ldd = 2048; dsto = WS_WGU; }
;         else if (t < 19200) { loc = t - 16384; ktn = 88; ldd = 5632; dsto = WS_WDN; }
;         else { loc = t - 19200; ktn = 32; ldd = 2048; dsto = WS_WMKV; }
;         const int n0 = (loc / ktn) * 64, k0 = (loc % ktn) * 64;
;         __syncthreads();
; #pragma unroll
;         for (int r = 0; r < 8; ++r) tile[(ty * 8 + r) * 65 + tx] = v[q][r];
;         __syncthreads();
;         const int nn = tid >> 3, kc = (tid & 7) * 8;
;         float w[8];
; #pragma unroll
;         for (int e = 0; e < 8; ++e) w[e] = tile[(kc + e) * 65 + nn];
;         u32x4 o; o[0] = cvt_pk(w[0], w[1]); o[1] = cvt_pk(w[2], w[3]); o[2] = cvt_pk(w[4], w[5]); o[3] = cvt_pk(w[6], w[7]);
;         *(u32x4*)((bf16_t*)(ws + dsto) + (size_t)(n0 + nn) * ldd + k0 + kc) = o;
.Lcvb_v1_t_s0_dd:
	s_waitcnt vmcnt(24)
	ds_write_b32 v5, v68
	ds_write_b32 v5, v69 offset:260
	ds_write_b32 v5, v70 offset:520
	ds_write_b32 v5, v71 offset:780
	ds_write_b32 v5, v72 offset:1040
	ds_write_b32 v5, v73 offset:1300
	ds_write_b32 v5, v74 offset:1560
	ds_write_b32 v5, v75 offset:1820
	s_waitcnt lgkmcnt(0)
	s_barrier
	ds_read_b32 v48, v6
	ds_read_b32 v49, v6 offset:260
	ds_read_b32 v50, v6 offset:520
	ds_read_b32 v51, v6 offset:780
	ds_read_b32 v52, v6 offset:1040
	ds_read_b32 v53, v6 offset:1300
	ds_read_b32 v54, v6 offset:1560
	ds_read_b32 v55, v6 offset:1820
	s_waitcnt lgkmcnt(0)
	v_cvt_pk_bf16_f32 v56, v48, v49
	v_cvt_pk_bf16_f32 v57, v50, v51
	v_cvt_pk_bf16_f32 v58, v52, v53
	v_cvt_pk_bf16_f32 v59, v54, v55
	global_store_dwordx4 v14, v[56:59], s[56:57]
	s_cmp_ge_i32 s63, 0x4b00
	s_cbranch_scc1 .Lcvb_v1_last
	s_add_i32 s47, s63, 0
	s_sub_i32 s54, s47, 0x4000
	s_mul_i32 s55, s54, 0xba3
	s_lshr_b32 s55, s55, 18
	s_mul_i32 s59, s55, 88
	s_sub_i32 s54, s54, s59
	s_lshl_b32 s54, s54, 6
	s_lshl_b32 s55, s55, 6
	s_mov_b32 s52, 0x2000
	v_readlane_b32 s48, v251, 28
	v_readlane_b32 s49, v251, 29
	s_mov_b32 s60, s54
	s_mul_i32 s60, s60, 0x2000
	s_lshl_b32 s61, s55, 2
	s_add_i32 s60, s60, s61
	s_add_u32 s48, s48, s60
	s_addc_u32 s49, s49, 0
	v_mad_u32_u24 v12, v2, s52, v0
	v_mov_b32_e32 v13, 0
	v_lshl_add_u64 v[12:13], s[48:49], 0, v[12:13]
.Lcvb_v1_n_l0_dd:
	global_load_dword v16, v[12:13], off nt
	v_lshl_add_u64 v[12:13], v[12:13], 0, s[52:53]
	global_load_dword v17, v[12:13], off nt
	v_lshl_add_u64 v[12:13], v[12:13], 0, s[52:53]
	global_load_dword v18, v[12:13], off nt
	v_lshl_add_u64 v[12:13], v[12:13], 0, s[52:53]
	global_load_dword v19, v[12:13], off nt
	v_lshl_add_u64 v[12:13], v[12:13], 0, s[52:53]
	global_load_dword v20, v[12:13], off nt
	v_lshl_add_u64 v[12:13], v[12:13], 0, s[52:53]
	global_load_dword v21, v[12:13], off nt
	v_lshl_add_u64 v[12:13], v[12:13], 0, s[52:53]
	global_load_dword v22, v[12:13], off nt
	v_lshl_add_u64 v[12:13], v[12:13], 0, s[52:53]
	global_load_dword v23, v[12:13], off nt
	s_add_i32 s47, s63, 1
	s_sub_i32 s54, s47, 0x4000
	s_mul_i32 s55, s54, 0xba3
	s_lshr_b32 s55, s55, 18
	s_mul_i32 s59, s55, 88
	s_sub_i32 s54, s54, s59
	s_lshl_b32 s54, s54, 6
	s_lshl_b32 s55, s55, 6
	s_mov_b32 s52, 0x2000
	v_readlane_b32 s48, v251, 28
	v_readlane_b32 s49, v251, 29
	s_mov_b32 s60, s54
	s_mul_i32 s60, s60, 0x2000
	s_lshl_b32 s61, s55, 2
	s_add_i32 s60, s60, s61
	s_add_u32 s48, s48, s60
	s_addc_u32 s49, s49, 0
	v_mad_u32_u24 v12, v2, s52, v0
	v_mov_b32_e32 v13, 0
	v_lshl_add_u64 v[12:13], s[48:49], 0, v[12:13]
.Lcvb_v1_n_l1_dd:
	global_load_dword v24, v[12:13], off nt
	v_lshl_add_u64 v[12:13], v[12:13], 0, s[52:53]
	global_load_dword v25, v[12:13], off nt
	v_lshl_add_u64 v[12:13], v[12:13], 0, s[52:53]
	global_load_dword v26, v[12:13], off nt
	v_lshl_add_u64 v[12:13], v[12:13], 0, s[52:53]
	global_load_dword v27, v[12:13], off nt
	v_lshl_add_u64 v[12:13], v[12:13], 0, s[52:53]
	global_load_dword v28, v[12:13], off nt
	v_lshl_add_u64 v[12:13], v[12:13], 0, s[52:53]
	global_load_dword v29, v[12:13], off nt
	v_lshl_add_u64 v[12:13], v[12:13], 0, s[52:53]
	global_load_dword v30, v[12:13], off nt
	v_lshl_add_u64 v[12:13], v[12:13], 0, s[52:53]
	global_load_dword v31, v[12:13], off nt
	s_add_i32 s47, s63, 2
	s_sub_i32 s54, s47, 0x4000
	s_mul_i32 s55, s54, 0xba3
	s_lshr_b32 s55, s55, 18
	s_mul_i32 s59, s55, 88
	s_sub_i32 s54, s54, s59
	s_lshl_b32 s54, s54, 6
	s_lshl_b32 s55, s55, 6
	s_mov_b32 s52, 0x2000
	v_readlane_b32 s48, v251, 28
	v_readlane_b32 s49, v251, 29
	s_mov_b32 s60, s54
	s_mul_i32 s60, s60, 0x2000
	s_lshl_b32 s61, s55, 2
	s_add_i32 s60, s60, s61
	s_add_u32 s48, s48, s60
	s_addc_u32 s49, s49, 0
	v_mad_u32_u24 v12, v2, s52, v0
	v_mov_b32_e32 v13, 0
	v_lshl_add_u64 v[12:13], s[48:49], 0, v[12:13]
.Lcvb_v1_n_l2_dd:
	global_load_dword v32, v[12:13], off nt
	v_lshl_add_u64 v[12:13], v[12:13], 0, s[52:53]
	global_load_dword v33, v[12:13], off nt
	v_lshl_add_u64 v[12:13], v[12:13], 0, s[52:53]
	global_load_dword v34, v[12:13], off nt
	v_lshl_add_u64 v[12:13], v[12:13], 0, s[52:53]
	global_load_dword v35, v[12:13], off nt
	v_lshl_add_u64 v[12:13], v[12:13], 0, s[52:53]
	global_load_dword v36, v[12:13], off nt
	v_lshl_add_u64 v[12:13], v[12:13], 0, s[52:53]
	global_load_dword v37, v[12:13], off nt
	v_lshl_add_u64 v[12:13], v[12:13], 0, s[52:53]
	global_load_dword v38, v[12:13], off nt
	v_lshl_add_u64 v[12:13], v[12:13], 0, s[52:53]
	global_load_dword v39, v[12:13], off nt
	s_add_i32 s47, s63, 3
	s_sub_i32 s54, s47, 0x4000
	s_mul_i32 s55, s54, 0xba3
	s_lshr_b32 s55, s55, 18
	s_mul_i32 s59, s55, 88
	s_sub_i32 s54, s54, s59
	s_lshl_b32 s54, s54, 6
	s_lshl_b32 s55, s55, 6
	s_mov_b32 s52, 0x2000
	v_readlane_b32 s48, v251, 28
	v_readlane_b32 s49, v251, 29
	s_mov_b32 s60, s54
	s_mul_i32 s60, s60, 0x2000
	s_lshl_b32 s61, s55, 2
	s_add_i32 s60, s60, s61
	s_add_u32 s48, s48, s60
	s_addc_u32 s49, s49, 0
	v_mad_u32_u24 v12, v2, s52, v0
	v_mov_b32_e32 v13, 0
	v_lshl_add_u64 v[12:13], s[48:49], 0, v[12:13]
; __device__ __forceinline__ unsigned cvt_pk(float lo, float hi) { const f32x2 v = {lo, hi}; const bf16x2_t b = __builtin_convertvector(v, bf16x2_t); return __builtin_bit_cast(unsigned, b); }
; template <int NT> __device__ __forceinline__ void conv_tilesN(const Params& p, LAS unsigned char* lds, int tid, int t0, int stride, int t_end) {
;     ...
;         const float* s0 = ptr + (size_t)(kk0 + ty * 8) * ld + col;
; #pragma unroll
;         for (int r = 0; r < 8; ++r) v[q][r] = __builtin_nontemporal_load(s0 + (size_t)r * ld);
;       }
;     }
; #pragma unroll
;     for (int q = 0; q < NT; ++q) {
;       const int t = t0 + q * stride;
;       if (t < t_end) {
;         int loc, ktn, ldd; size_t dsto;
;         if (t < 7680) { loc = t; ktn = 32; ldd = 2048; dsto = WS_WIN; }
;         else if (t < 9728) { loc = t - 7680; ktn = 64; ldd = 4096; dsto = WS_WCAT; }
;         else if (t < 10752) { loc = t - 9728; ktn = 32; ldd = 2048; dsto = WS_WOUT; }
;         else if (t < 16384) { loc = t - 10752; ktn = 32; ldd = 2048; dsto = WS_WGU; }
;         else if (t < 19200) { loc = t - 16384; ktn = 88; ldd = 5632; dsto = WS_WDN; }
;         else { loc = t - 19200; ktn = 32; ldd = 2048; dsto = WS_WMKV; }
;         const int n0 = (loc / ktn) * 64, k0 = (loc % ktn) * 64;
;         __syncthreads();
; #pragma unroll
;         for (int r = 0; r < 8; ++r) tile[(ty * 8 + r) * 65 + tx] = v[q][r];
;         __syncthreads();
;         const int nn = tid >> 3, kc = (tid & 7) * 8;
;         float w[8];
; #pragma unroll
;         for (int e = 0; e < 8; ++e) w[e] = tile[(kc + e) * 65 + nn];
;         u32x4 o; o[0] = cvt_pk(w[0], w[1]); o[1] = cvt_pk(w[2], w[3]); o[2] = cvt_pk(w[4], w[5]); o[3] = cvt_pk(w[6], w[7]);
;         *(u32x4*)((bf16_t*)(ws + dsto) + (size_t)(n0 + nn) * ldd + k0 + kc) = o;
.Lcvb_v1_n_l3_dd:
	global_load_dword v40, v[12:13], off nt
	v_lshl_add_u64 v[12:13], v[12:13], 0, s[52:53]
	global_load_dword v41, v[12:13], off nt
	v_lshl_add_u64 v[12:13], v[12:13], 0, s[52:53]
	global_load_dword v42, v[12:13], off nt
	v_lshl_add_u64 v[12:13], v[12:13], 0, s[52:53]
	global_load_dword v43, v[12:13], off nt
	v_lshl_add_u64 v[12:13], v[12:13], 0, s[52:53]
	global_load_dword v44, v[12:13], off nt
	v_lshl_add_u64 v[12:13], v[12:13], 0, s[52:53]
	global_load_dword v45, v[12:13], off nt
	v_lshl_add_u64 v[12:13], v[12:13], 0, s[52:53]
	global_load_dword v46, v[12:13], off nt
	v_lshl_add_u64 v[12:13], v[12:13], 0, s[52:53]
	global_load_dword v47, v[12:13], off nt
	s_add_i32 s47, s46, 1
	s_sub_i32 s54, s47, 0x4000
	s_mul_i32 s55, s54, 0xba3
	s_lshr_b32 s55, s55, 18
	s_mul_i32 s59, s55, 88
	s_sub_i32 s54, s54, s59
	s_lshl_b32 s54, s54, 6
	s_lshl_b32 s55, s55, 6
	s_mov_b32 s58, 0x2c00
	s_mul_i32 s60, s55, 0x2c00
	s_lshl_b32 s61, s54, 1
	s_add_i32 s60, s60, s61
	s_add_u32 s56, s24, 0xa509000
	s_addc_u32 s57, s25, 0
	s_add_u32 s56, s56, s60
	s_addc_u32 s57, s57, 0
	v_mad_u32_u24 v14, v3, s58, v4
.Lcvb_v1_a_s1_dd:
	s_barrier
	s_waitcnt vmcnt(48)
	ds_write_b32 v5, v76
	ds_write_b32 v5, v77 offset:260
	ds_write_b32 v5, v78 offset:520
	ds_write_b32 v5, v79 offset:780
	ds_write_b32 v5, v80 offset:1040
	ds_write_b32 v5, v81 offset:1300
	ds_write_b32 v5, v82 offset:1560
	ds_write_b32 v5, v83 offset:1820
	s_waitcnt lgkmcnt(0)
	s_barrier
	ds_read_b32 v48, v6
	ds_read_b32 v49, v6 offset:260
	ds_read_b32 v50, v6 offset:520
	ds_read_b32 v51, v6 offset:780
	ds_read_b32 v52, v6 offset:1040
	ds_read_b32 v53, v6 offset:1300
	ds_read_b32 v54, v6 offset:1560
	ds_read_b32 v55, v6 offset:1820
	s_waitcnt lgkmcnt(0)
	v_cvt_pk_bf16_f32 v56, v48, v49
	v_cvt_pk_bf16_f32 v57, v50, v51
	v_cvt_pk_bf16_f32 v58, v52, v53
	v_cvt_pk_bf16_f32 v59, v54, v55
	global_store_dwordx4 v14, v[56:59], s[56:57]
	s_add_i32 s47, s46, 2
	s_sub_i32 s54, s47, 0x4000
	s_mul_i32 s55, s54, 0xba3
	s_lshr_b32 s55, s55, 18
	s_mul_i32 s59, s55, 88
	s_sub_i32 s54, s54, s59
	s_lshl_b32 s54, s54, 6
	s_lshl_b32 s55, s55, 6
	s_mov_b32 s58, 0x2c00
	s_mul_i32 s60, s55, 0x2c00
	s_lshl_b32 s61, s54, 1
	s_add_i32 s60, s60, s61
	s_add_u32 s56, s24, 0xa509000
	s_addc_u32 s57, s25, 0
	s_add_u32 s56, s56, s60
	s_addc_u32 s57, s57, 0
	v_mad_u32_u24 v14, v3, s58, v4
.Lcvb_v1_a_s2_dd:
	s_barrier
	s_waitcnt vmcnt(40)
	ds_write_b32 v5, v84
	ds_write_b32 v5, v85 offset:260
	ds_write_b32 v5, v86 offset:520
	ds_write_b32 v5, v87 offset:780
	ds_write_b32 v5, v88 offset:1040
	ds_write_b32 v5, v89 offset:1300
	ds_write_b32 v5, v90 offset:1560
	ds_write_b32 v5, v91 offset:1820
	s_waitcnt lgkmcnt(0)
	s_barrier
	ds_read_b32 v48, v6
	ds_read_b32 v49, v6 offset:260
	ds_read_b32 v50, v6 offset:520
	ds_read_b32 v51, v6 offset:780
	ds_read_b32 v52, v6 offset:1040
	ds_read_b32 v53, v6 offset:1300
	ds_read_b32 v54, v6 offset:1560
	ds_read_b32 v55, v6 offset:1820
	s_waitcnt lgkmcnt(0)
	v_cvt_pk_bf16_f32 v56, v48, v49
	v_cvt_pk_bf16_f32 v57, v50, v51
	v_cvt_pk_bf16_f32 v58, v52, v53
	v_cvt_pk_bf16_f32 v59, v54, v55
	global_store_dwordx4 v14, v[56:59], s[56:57]
	s_add_i32 s47, s46, 3
	s_sub_i32 s54, s47, 0x4000
	s_mul_i32 s55, s54, 0xba3
	s_lshr_b32 s55, s55, 18
	s_mul_i32 s59, s55, 88
	s_sub_i32 s54, s54, s59
	s_lshl_b32 s54, s54, 6
	s_lshl_b32 s55, s55, 6
	s_mov_b32 s58, 0x2c00
	s_mul_i32 s60, s55, 0x2c00
	s_lshl_b32 s61, s54, 1
	s_add_i32 s60, s60, s61
	s_add_u32 s56, s24, 0xa509000
	s_addc_u32 s57, s25, 0
	s_add_u32 s56, s56, s60
	s_addc_u32 s57, s57, 0
	v_mad_u32_u24 v14, v3, s58, v4
.Lcvb_v1_a_s3_dd:
	s_barrier
	s_waitcnt vmcnt(32)
	ds_write_b32 v5, v92
	ds_write_b32 v5, v93 offset:260
	ds_write_b32 v5, v94 offset:520
	ds_write_b32 v5, v95 offset:780
	ds_write_b32 v5, v96 offset:1040
	ds_write_b32 v5, v97 offset:1300
	ds_write_b32 v5, v98 offset:1560
	ds_write_b32 v5, v99 offset:1820
	s_waitcnt lgkmcnt(0)
	s_barrier
	ds_read_b32 v48, v6
	ds_read_b32 v49, v6 offset:260
	ds_read_b32 v50, v6 offset:520
	ds_read_b32 v51, v6 offset:780
	ds_read_b32 v52, v6 offset:1040
	ds_read_b32 v53, v6 offset:1300
	ds_read_b32 v54, v6 offset:1560
	ds_read_b32 v55, v6 offset:1820
	s_waitcnt lgkmcnt(0)
	v_cvt_pk_bf16_f32 v56, v48, v49
	v_cvt_pk_bf16_f32 v57, v50, v51
	v_cvt_pk_bf16_f32 v58, v52, v53
	v_cvt_pk_bf16_f32 v59, v54, v55
	global_store_dwordx4 v14, v[56:59], s[56:57]
	s_mov_b32 s46, s63
	s_branch .Lcvb_v0_top

; #define LAS __attribute__((address_space(3)))
; __device__ __forceinline__ unsigned cvt_pk(float lo, float hi) { const f32x2 v = {lo, hi}; const bf16x2_t b = __builtin_convertvector(v, bf16x2_t); return __builtin_bit_cast(unsigned, b); }
; template <int NT> __device__ __forceinline__ void conv_tilesN(const Params& p, LAS unsigned char* lds, int tid, int t0, int stride, int t_end) {
;     ...
;         __syncthreads();
; #pragma unroll
;         for (int r = 0; r < 8; ++r) tile[(ty * 8 + r) * 65 + tx] = v[q][r];
;         __syncthreads();
;         const int nn = tid >> 3, kc = (tid & 7) * 8;
;         float w[8];
; #pragma unroll
;         for (int e = 0; e < 8; ++e) w[e] = tile[(kc + e) * 65 + nn];
;         u32x4 o; o[0] = cvt_pk(w[0], w[1]); o[1] = cvt_pk(w[2], w[3]); o[2] = cvt_pk(w[4], w[5]); o[3] = cvt_pk(w[6], w[7]);
;         *(u32x4*)((bf16_t*)(ws + dsto) + (size_t)(n0 + nn) * ldd + k0 + kc) = o;
; __device__ __forceinline__ void conv_queue(const Params& p, LAS unsigned char* lds, unsigned* ctr, int t_begin, int t_end) {
;   int tid = threadIdx.x; asm volatile("" : "+v"(tid));
;   LAS unsigned* slot = (LAS unsigned*)(lds + LDS_CTL);
;   unsigned nxt = 0u;
;   if (tid == 0) nxt = atomicAdd(ctr, 4u);
.Lcvb_v1_b_s1_dd:
	s_barrier
	s_waitcnt vmcnt(16)
	ds_write_b32 v5, v76
	ds_write_b32 v5, v77 offset:260
	ds_write_b32 v5, v78 offset:520
	ds_write_b32 v5, v79 offset:780
	ds_write_b32 v5, v80 offset:1040
	ds_write_b32 v5, v81 offset:1300
	ds_write_b32 v5, v82 offset:1560
	ds_write_b32 v5, v83 offset:1820
	s_waitcnt lgkmcnt(0)
	s_barrier
	ds_read_b32 v48, v6
	ds_read_b32 v49, v6 offset:260
	ds_read_b32 v50, v6 offset:520
	ds_read_b32 v51, v6 offset:780
	ds_read_b32 v52, v6 offset:1040
	ds_read_b32 v53, v6 offset:1300
	ds_read_b32 v54, v6 offset:1560
	ds_read_b32 v55, v6 offset:1820
	s_waitcnt lgkmcnt(0)
	v_cvt_pk_bf16_f32 v56, v48, v49
	v_cvt_pk_bf16_f32 v57, v50, v51
	v_cvt_pk_bf16_f32 v58, v52, v53
	v_cvt_pk_bf16_f32 v59, v54, v55
	global_store_dwordx4 v14, v[56:59], s[56:57]
	s_add_i32 s47, s46, 2
	s_sub_i32 s54, s47, 0x4000
	s_mul_i32 s55, s54, 0xba3
	s_lshr_b32 s55, s55, 18
	s_mul_i32 s59, s55, 88
	s_sub_i32 s54, s54, s59
	s_lshl_b32 s54, s54, 6
	s_lshl_b32 s55, s55, 6
	s_mov_b32 s58, 0x2c00
	s_mul_i32 s60, s55, 0x2c00
	s_lshl_b32 s61, s54, 1
	s_add_i32 s60, s60, s61
	s_add_u32 s56, s24, 0xa509000
	s_addc_u32 s57, s25, 0
	s_add_u32 s56, s56, s60
	s_addc_u32 s57, s57, 0
	v_mad_u32_u24 v14, v3, s58, v4
.Lcvb_v1_b_s2_dd:
	s_barrier
	s_waitcnt vmcnt(8)
	ds_write_b32 v5, v84
	ds_write_b32 v5, v85 offset:260
	ds_write_b32 v5, v86 offset:520
	ds_write_b32 v5, v87 offset:780
	ds_write_b32 v5, v88 offset:1040
	ds_write_b32 v5, v89 offset:1300
	ds_write_b32 v5, v90 offset:1560
	ds_write_b32 v5, v91 offset:1820
	s_waitcnt lgkmcnt(0)
	s_barrier
	ds_read_b32 v48, v6
	ds_read_b32 v49, v6 offset:260
	ds_read_b32 v50, v6 offset:520
	ds_read_b32 v51, v6 offset:780
	ds_read_b32 v52, v6 offset:1040
	ds_read_b32 v53, v6 offset:1300
	ds_read_b32 v54, v6 offset:1560
	ds_read_b32 v55, v6 offset:1820
	s_waitcnt lgkmcnt(0)
	v_cvt_pk_bf16_f32 v56, v48, v49
	v_cvt_pk_bf16_f32 v57, v50, v51
	v_cvt_pk_bf16_f32 v58, v52, v53
	v_cvt_pk_bf16_f32 v59, v54, v55
	global_store_dwordx4 v14, v[56:59], s[56:57]
	s_add_i32 s47, s46, 3
	s_sub_i32 s54, s47, 0x4000
	s_mul_i32 s55, s54, 0xba3
	s_lshr_b32 s55, s55, 18
	s_mul_i32 s59, s55, 88
	s_sub_i32 s54, s54, s59
	s_lshl_b32 s54, s54, 6
	s_lshl_b32 s55, s55, 6
	s_mov_b32 s58, 0x2c00
	s_mul_i32 s60, s55, 0x2c00
	s_lshl_b32 s61, s54, 1
	s_add_i32 s60, s60, s61
	s_add_u32 s56, s24, 0xa509000
	s_addc_u32 s57, s25, 0
	s_add_u32 s56, s56, s60
	s_addc_u32 s57, s57, 0
	v_mad_u32_u24 v14, v3, s58, v4
.Lcvb_v1_b_s3_dd:
	s_barrier
	s_waitcnt vmcnt(0)
	ds_write_b32 v5, v92
	ds_write_b32 v5, v93 offset:260
	ds_write_b32 v5, v94 offset:520
	ds_write_b32 v5, v95 offset:780
	ds_write_b32 v5, v96 offset:1040
	ds_write_b32 v5, v97 offset:1300
	ds_write_b32 v5, v98 offset:1560
	ds_write_b32 v5, v99 offset:1820
	s_waitcnt lgkmcnt(0)
	s_barrier
	ds_read_b32 v48, v6
	ds_read_b32 v49, v6 offset:260
	ds_read_b32 v50, v6 offset:520
	ds_read_b32 v51, v6 offset:780
	ds_read_b32 v52, v6 offset:1040
	ds_read_b32 v53, v6 offset:1300
	ds_read_b32 v54, v6 offset:1560
	ds_read_b32 v55, v6 offset:1820
	s_waitcnt lgkmcnt(0)
	v_cvt_pk_bf16_f32 v56, v48, v49
	v_cvt_pk_bf16_f32 v57, v50, v51
	v_cvt_pk_bf16_f32 v58, v52, v53
	v_cvt_pk_bf16_f32 v59, v54, v55
	global_store_dwordx4 v14, v[56:59], s[56:57]
	s_branch .Lcvb_done
.Lcvb_done:
	s_waitcnt vmcnt(0) lgkmcnt(0)
	s_branch .LBB0_1198
	v_mov_b32_e32 v0, v226
	v_mov_b32_e32 v11, 0
	v_cmp_eq_u32_e64 s[36:37], 0, v0
	s_and_saveexec_b64 s[40:41], s[36:37]
	s_cbranch_execz .LBB0_999
	s_mov_b64 s[46:47], exec
	v_mbcnt_lo_u32_b32 v1, s46, 0
	v_mbcnt_hi_u32_b32 v1, s47, v1
	v_cmp_eq_u32_e32 vcc, 0, v1
	s_and_saveexec_b64 s[44:45], vcc
	s_cbranch_execz .LBB0_998
	s_bcnt1_i32_b64 s29, s[46:47]
	s_lshl_b32 s29, s29, 2
	v_mov_b32_e32 v2, s29
	global_atomic_add v2, v65, v2, s[24:25] offset:20 sc0

; #define LAS __attribute__((address_space(3)))
; __device__ __forceinline__ unsigned xb_ld(unsigned* p)              { return __hip_atomic_load(p, __ATOMIC_RELAXED, __HIP_MEMORY_SCOPE_AGENT); }
; __device__ __forceinline__ void conv_queue(const Params& p, LAS unsigned char* lds, unsigned* ctr, int t_begin, int t_end) {
;   int tid = threadIdx.x; asm volatile("" : "+v"(tid));
;   LAS unsigned* slot = (LAS unsigned*)(lds + LDS_CTL);
;   unsigned nxt = 0u;
;   if (tid == 0) nxt = atomicAdd(ctr, 4u);
; __device__ __forceinline__ void xcd_barrier_complete(unsigned* bar, unsigned x, unsigned& nloc, unsigned& nx) {
;     ...
;     for (;;) {
;         sum = 0u; cnt = 0u; mine = 0u;
; #pragma unroll
;         for (unsigned j = 0; j < 16; ++j) { const unsigned c = xb_ld(&bar[XB_XCNT(j)]); sum += c; cnt += (c > 0u) ? 1u : 0u; mine = (j == x) ? c : mine; }
;         if (sum == G) break;
;         __builtin_amdgcn_s_sleep(1);
;         if ((++sp & 255u) == 0u) { if (xb_ld(&bar[XB_TMO])) break; if (sp > XB_SPIN_CAP) { atomicAdd(&bar[XB_TMO], 1u); break; } }
.LBB0_1209:
	s_cmp_lt_u32 s29, 0x40001
	s_mov_b64 s[40:41], 0
	s_cselect_b64 s[44:45], -1, 0
	s_and_b64 vcc, exec, s[44:45]
	s_cbranch_vccnz .LBB0_1206
	s_branch .LBB0_1202
.LBB0_1210:
	s_branch .Lcva_entry
.Lcva_entry:
	v_and_b32_e32 v0, 63, v226
	v_lshrrev_b32_e32 v2, 6, v226
	v_lshlrev_b32_e32 v2, 3, v2
	v_lshrrev_b32_e32 v3, 3, v226
	v_and_b32_e32 v4, 7, v226
	v_lshlrev_b32_e32 v4, 3, v4
	v_mul_u32_u24_e32 v5, 0x41, v2
	v_add_u32_e32 v5, v5, v0
	v_lshlrev_b32_e32 v5, 2, v5
	v_mul_u32_u24_e32 v6, 0x41, v4
	v_add_u32_e32 v6, v6, v3
	v_lshlrev_b32_e32 v6, 2, v6
	v_lshlrev_b32_e32 v4, 1, v4
	v_lshrrev_b32_e32 v1, 5, v0
	v_lshlrev_b32_e32 v1, 4, v1
	v_and_b32_e32 v7, 15, v0
	v_or_b32_e32 v1, v1, v7
	v_lshlrev_b32_e32 v1, 2, v1
	v_and_b32_e32 v7, 16, v0
	v_lshlrev_b32_e32 v0, 2, v0
	v_mov_b32_e32 v8, 0x25ff0
	v_mov_b32_e32 v9, 4
	v_mov_b32_e32 v10, 0
	v_cmp_eq_u32_e64 s[44:45], 0, v226
	s_mov_b32 s53, 0
	s_and_saveexec_b64 s[40:41], s[44:45]
	s_cbranch_execz .Lcva_f0_a
	global_atomic_add v10, v65, v9, s[24:25] offset:16 sc0

; template <int NT> __device__ __forceinline__ void conv_tilesN(const Params& p, LAS unsigned char* lds, int tid, int t0, int stride, int t_end) {
;     ...
;         int mat, loc, ktn;
;         if (t < 7680) { mat = 0; loc = t; ktn = 32; }
;         else if (t < 9728) { mat = 1; loc = t - 7680; ktn = 64; }
;         else if (t < 10752) { mat = 2; loc = t - 9728; ktn = 32; }
;         else if (t < 16384) { mat = 3; loc = t - 10752; ktn = 32; }
;         else if (t < 19200) { mat = 4; loc = t - 16384; ktn = 88; }
;         else { mat = 5; loc = t - 19200; ktn = 32; }
;         const int n0 = (loc / ktn) * 64, k0 = (loc % ktn) * 64;
;         const int n = n0 + tx;
;         const float* ptr; int ld, col, kk0 = k0;
;         if (mat == 0) {
;           ptr = p.in[6]; ld = INW; col = n;
;           if (n >= OFF_RQ && n < OFF_RV) { const int s = n & 127; col = (n & ~127) + ((s >> 4) & 1) * 64 + (s >> 5) * 16 + (s & 15); }
;         } else if (mat == 1) {
;           ld = 2048; col = n;
;           if (k0 < 1024) { ptr = p.in[11]; } else if (k0 < 3072) { ptr = p.in[13]; kk0 = k0 - 1024; } else { ptr = p.in[16]; kk0 = k0 - 3072; }
;         } else if (mat == 2) { ptr = p.in[17]; ld = 2048; col = n; }
;         else if (mat == 3) {
;           const int T = n >> 8, s = n & 255;
;           const int f = 128 * T + 64 * (s >> 7) + 16 * ((s >> 5) & 3) + (s & 15);
;           ptr = ((s >> 4) & 1) ? p.in[21] : p.in[20]; ld = DFF; col = f;
;         } else if (mat == 4) { ptr = p.in[22]; ld = 2048; col = n; }
;         else { if (n < 1024) { ptr = p.in[14]; col = n; } else { ptr = p.in[15]; col = n - 1024; } ld = 1024; }
;         const float* s0 = ptr + (size_t)(kk0 + ty * 8) * ld + col;
; #pragma unroll
;         for (int r = 0; r < 8; ++r) v[q][r] = __builtin_nontemporal_load(s0 + (size_t)r * ld);
; __device__ __forceinline__ void conv_queue(const Params& p, LAS unsigned char* lds, unsigned* ctr, int t_begin, int t_end) {
;     ...
;   unsigned nxt = 0u;
;   if (tid == 0) nxt = atomicAdd(ctr, 4u);
;   for (;;) {
;     __syncthreads();
;     if (tid == 0) *slot = nxt;
;     __syncthreads();
;     const int base = t_begin + (int)__builtin_amdgcn_readfirstlane(*slot);
;     if (base >= t_end) break;
;     if (tid == 0) nxt = atomicAdd(ctr, 4u);
.Lcva_x0_w:
	s_mov_b64 exec, s[40:41]
	s_waitcnt lgkmcnt(0)
	s_barrier
	ds_read_b32 v11, v8
	s_waitcnt lgkmcnt(0)
	s_nop 0
	v_readfirstlane_b32 s46, v11
	s_nop 1
	s_add_i32 s46, s46, 0x1e00
	s_cmp_ge_i32 s46, 0x4000
	s_cbranch_scc1 .Lcva_done
	s_and_saveexec_b64 s[40:41], s[44:45]
	s_cbranch_execz .Lcva_f1_a
	global_atomic_add v10, v65, v9, s[24:25] offset:16 sc0
.Lcva_f1_a:
	s_mov_b64 exec, s[40:41]
	s_add_i32 s47, s46, 0
	s_cmp_lt_u32 s47, 0x2600
	s_cbranch_scc0 .Lcva_p_l0_m1
	s_sub_i32 s54, s47, 0x1e00
	s_lshr_b32 s55, s54, 6
	s_lshl_b32 s55, s55, 6
	s_and_b32 s54, s54, 63
	s_lshl_b32 s54, s54, 6
	s_mov_b32 s52, 0x2000
	s_cmpk_lt_u32 s54, 0x400
	s_cbranch_scc0 .Lcva_p_l0_k1
	v_readlane_b32 s48, v251, 6
	v_readlane_b32 s49, v251, 7
	s_mov_b32 s60, s54
	s_branch .Lcva_p_l0_k3
.Lcva_p_l0_k1:
	s_cmpk_lt_u32 s54, 0xc00
	s_cbranch_scc0 .Lcva_p_l0_k2
	v_readlane_b32 s48, v251, 10
	v_readlane_b32 s49, v251, 11
	s_sub_i32 s60, s54, 0x400
	s_branch .Lcva_p_l0_k3
.Lcva_p_l0_k2:
	v_readlane_b32 s48, v251, 16
	v_readlane_b32 s49, v251, 17
	s_sub_i32 s60, s54, 0xc00
.Lcva_p_l0_k3:
	s_mul_i32 s60, s60, 0x2000
	s_lshl_b32 s61, s55, 2
	s_add_i32 s60, s60, s61
	s_add_u32 s48, s48, s60
	s_addc_u32 s49, s49, 0
	v_mad_u32_u24 v12, v2, s52, v0
	v_mov_b32_e32 v13, 0
	v_lshl_add_u64 v[12:13], s[48:49], 0, v[12:13]
	s_branch .Lcva_p_l0_dd
.Lcva_p_l0_m1:
	s_cmp_lt_u32 s47, 0x2a00
	s_cbranch_scc0 .Lcva_p_l0_m2
	s_sub_i32 s54, s47, 0x2600
	s_lshr_b32 s55, s54, 5
	s_lshl_b32 s55, s55, 6
	s_and_b32 s54, s54, 31
	s_lshl_b32 s54, s54, 6
	s_mov_b32 s52, 0x2000
	v_readlane_b32 s48, v251, 18
	v_readlane_b32 s49, v251, 19
	s_mov_b32 s60, s54
	s_mul_i32 s60, s60, 0x2000
	s_lshl_b32 s61, s55, 2
	s_add_i32 s60, s60, s61
	s_add_u32 s48, s48, s60
	s_addc_u32 s49, s49, 0
	v_mad_u32_u24 v12, v2, s52, v0
	v_mov_b32_e32 v13, 0
	v_lshl_add_u64 v[12:13], s[48:49], 0, v[12:13]
	s_branch .Lcva_p_l0_dd
.Lcva_p_l0_m2:
	s_sub_i32 s54, s47, 0x2a00
	s_lshr_b32 s55, s54, 5
	s_mov_b32 s59, s55
	s_lshl_b32 s55, s55, 6
	s_and_b32 s54, s54, 31
	s_lshl_b32 s54, s54, 6
	s_mov_b32 s52, 0x5800
	s_lshr_b32 s60, s59, 2
	s_lshl_b32 s60, s60, 7
	s_bfe_u32 s61, s59, 0x10001
	s_lshl_b32 s61, s61, 6
	s_add_i32 s60, s60, s61
	s_and_b32 s61, s59, 1
	s_lshl_b32 s61, s61, 5
	s_add_i32 s60, s60, s61
	s_lshl_b32 s60, s60, 2
	s_mul_i32 s61, s54, 0x5800
	s_add_i32 s60, s60, s61
	v_readlane_b32 s48, v251, 24
	v_readlane_b32 s49, v251, 25
	v_readlane_b32 s50, v251, 26
	v_readlane_b32 s51, v251, 27
	s_add_u32 s48, s48, s60
	s_addc_u32 s49, s49, 0
	s_add_u32 s50, s50, s60
	s_addc_u32 s51, s51, 0
	v_mad_u32_u24 v12, v2, s52, v1
	v_cmp_ne_u32_e32 vcc, 0, v7
	v_mov_b32_e32 v14, s48
	v_mov_b32_e32 v15, s49
	v_mov_b32_e32 v62, s50
	v_mov_b32_e32 v63, s51
	v_cndmask_b32_e32 v14, v14, v62, vcc
	v_cndmask_b32_e32 v15, v15, v63, vcc
	v_mov_b32_e32 v13, 0
	v_lshl_add_u64 v[12:13], v[14:15], 0, v[12:13]
.Lcva_p_l0_dd:
	global_load_dword v16, v[12:13], off nt
	v_lshl_add_u64 v[12:13], v[12:13], 0, s[52:53]
	global_load_dword v17, v[12:13], off nt
	v_lshl_add_u64 v[12:13], v[12:13], 0, s[52:53]
	global_load_dword v18, v[12:13], off nt
	v_lshl_add_u64 v[12:13], v[12:13], 0, s[52:53]
	global_load_dword v19, v[12:13], off nt
	v_lshl_add_u64 v[12:13], v[12:13], 0, s[52:53]
	global_load_dword v20, v[12:13], off nt
	v_lshl_add_u64 v[12:13], v[12:13], 0, s[52:53]
	global_load_dword v21, v[12:13], off nt
	v_lshl_add_u64 v[12:13], v[12:13], 0, s[52:53]
	global_load_dword v22, v[12:13], off nt
	v_lshl_add_u64 v[12:13], v[12:13], 0, s[52:53]
	global_load_dword v23, v[12:13], off nt
	s_add_i32 s47, s46, 1
	s_cmp_lt_u32 s47, 0x2600
	s_cbranch_scc0 .Lcva_p_l1_m1
	s_sub_i32 s54, s47, 0x1e00
	s_lshr_b32 s55, s54, 6
	s_lshl_b32 s55, s55, 6
	s_and_b32 s54, s54, 63
	s_lshl_b32 s54, s54, 6
	s_mov_b32 s52, 0x2000
	s_cmpk_lt_u32 s54, 0x400
	s_cbranch_scc0 .Lcva_p_l1_k1
	v_readlane_b32 s48, v251, 6
	v_readlane_b32 s49, v251, 7
	s_mov_b32 s60, s54
	s_branch .Lcva_p_l1_k3

; template <int NT> __device__ __forceinline__ void conv_tilesN(const Params& p, LAS unsigned char* lds, int tid, int t0, int stride, int t_end) {
;     ...
;         int mat, loc, ktn;
;         if (t < 7680) { mat = 0; loc = t; ktn = 32; }
;         else if (t < 9728) { mat = 1; loc = t - 7680; ktn = 64; }
;         else if (t < 10752) { mat = 2; loc = t - 9728; ktn = 32; }
;         else if (t < 16384) { mat = 3; loc = t - 10752; ktn = 32; }
;         else if (t < 19200) { mat = 4; loc = t - 16384; ktn = 88; }
;         else { mat = 5; loc = t - 19200; ktn = 32; }
;         const int n0 = (loc / ktn) * 64, k0 = (loc % ktn) * 64;
;         const int n = n0 + tx;
;         const float* ptr; int ld, col, kk0 = k0;
;         if (mat == 0) {
;           ptr = p.in[6]; ld = INW; col = n;
;           if (n >= OFF_RQ && n < OFF_RV) { const int s = n & 127; col = (n & ~127) + ((s >> 4) & 1) * 64 + (s >> 5) * 16 + (s & 15); }
;         } else if (mat == 1) {
;           ld = 2048; col = n;
;           if (k0 < 1024) { ptr = p.in[11]; } else if (k0 < 3072) { ptr = p.in[13]; kk0 = k0 - 1024; } else { ptr = p.in[16]; kk0 = k0 - 3072; }
;         } else if (mat == 2) { ptr = p.in[17]; ld = 2048; col = n; }
;         else if (mat == 3) {
;           const int T = n >> 8, s = n & 255;
;           const int f = 128 * T + 64 * (s >> 7) + 16 * ((s >> 5) & 3) + (s & 15);
;           ptr = ((s >> 4) & 1) ? p.in[21] : p.in[20]; ld = DFF; col = f;
;         } else if (mat == 4) { ptr = p.in[22]; ld = 2048; col = n; }
;         else { if (n < 1024) { ptr = p.in[14]; col = n; } else { ptr = p.in[15]; col = n - 1024; } ld = 1024; }
;         const float* s0 = ptr + (size_t)(kk0 + ty * 8) * ld + col;
; #pragma unroll
;         for (int r = 0; r < 8; ++r) v[q][r] = __builtin_nontemporal_load(s0 + (size_t)r * ld);
.Lcva_p_l1_dd:
	global_load_dword v24, v[12:13], off nt
	v_lshl_add_u64 v[12:13], v[12:13], 0, s[52:53]
	global_load_dword v25, v[12:13], off nt
	v_lshl_add_u64 v[12:13], v[12:13], 0, s[52:53]
	global_load_dword v26, v[12:13], off nt
	v_lshl_add_u64 v[12:13], v[12:13], 0, s[52:53]
	global_load_dword v27, v[12:13], off nt
	v_lshl_add_u64 v[12:13], v[12:13], 0, s[52:53]
	global_load_dword v28, v[12:13], off nt
	v_lshl_add_u64 v[12:13], v[12:13], 0, s[52:53]
	global_load_dword v29, v[12:13], off nt
	v_lshl_add_u64 v[12:13], v[12:13], 0, s[52:53]
	global_load_dword v30, v[12:13], off nt
	v_lshl_add_u64 v[12:13], v[12:13], 0, s[52:53]
	global_load_dword v31, v[12:13], off nt
	s_add_i32 s47, s46, 2
	s_cmp_lt_u32 s47, 0x2600
	s_cbranch_scc0 .Lcva_p_l2_m1
	s_sub_i32 s54, s47, 0x1e00
	s_lshr_b32 s55, s54, 6
	s_lshl_b32 s55, s55, 6
	s_and_b32 s54, s54, 63
	s_lshl_b32 s54, s54, 6
	s_mov_b32 s52, 0x2000
	s_cmpk_lt_u32 s54, 0x400
	s_cbranch_scc0 .Lcva_p_l2_k1
	v_readlane_b32 s48, v251, 6
	v_readlane_b32 s49, v251, 7
	s_mov_b32 s60, s54
	s_branch .Lcva_p_l2_k3

; template <int NT> __device__ __forceinline__ void conv_tilesN(const Params& p, LAS unsigned char* lds, int tid, int t0, int stride, int t_end) {
;     ...
;         int mat, loc, ktn;
;         if (t < 7680) { mat = 0; loc = t; ktn = 32; }
;         else if (t < 9728) { mat = 1; loc = t - 7680; ktn = 64; }
;         else if (t < 10752) { mat = 2; loc = t - 9728; ktn = 32; }
;         else if (t < 16384) { mat = 3; loc = t - 10752; ktn = 32; }
;         else if (t < 19200) { mat = 4; loc = t - 16384; ktn = 88; }
;         else { mat = 5; loc = t - 19200; ktn = 32; }
;         const int n0 = (loc / ktn) * 64, k0 = (loc % ktn) * 64;
;         const int n = n0 + tx;
;         const float* ptr; int ld, col, kk0 = k0;
;         if (mat == 0) {
;           ptr = p.in[6]; ld = INW; col = n;
;           if (n >= OFF_RQ && n < OFF_RV) { const int s = n & 127; col = (n & ~127) + ((s >> 4) & 1) * 64 + (s >> 5) * 16 + (s & 15); }
;         } else if (mat == 1) {
;           ld = 2048; col = n;
;           if (k0 < 1024) { ptr = p.in[11]; } else if (k0 < 3072) { ptr = p.in[13]; kk0 = k0 - 1024; } else { ptr = p.in[16]; kk0 = k0 - 3072; }
;         } else if (mat == 2) { ptr = p.in[17]; ld = 2048; col = n; }
;         else if (mat == 3) {
;           const int T = n >> 8, s = n & 255;
;           const int f = 128 * T + 64 * (s >> 7) + 16 * ((s >> 5) & 3) + (s & 15);
;           ptr = ((s >> 4) & 1) ? p.in[21] : p.in[20]; ld = DFF; col = f;
;         } else if (mat == 4) { ptr = p.in[22]; ld = 2048; col = n; }
;         else { if (n < 1024) { ptr = p.in[14]; col = n; } else { ptr = p.in[15]; col = n - 1024; } ld = 1024; }
;         const float* s0 = ptr + (size_t)(kk0 + ty * 8) * ld + col;
; #pragma unroll
;         for (int r = 0; r < 8; ++r) v[q][r] = __builtin_nontemporal_load(s0 + (size_t)r * ld);
.Lcva_p_l2_dd:
	global_load_dword v32, v[12:13], off nt
	v_lshl_add_u64 v[12:13], v[12:13], 0, s[52:53]
	global_load_dword v33, v[12:13], off nt
	v_lshl_add_u64 v[12:13], v[12:13], 0, s[52:53]
	global_load_dword v34, v[12:13], off nt
	v_lshl_add_u64 v[12:13], v[12:13], 0, s[52:53]
	global_load_dword v35, v[12:13], off nt
	v_lshl_add_u64 v[12:13], v[12:13], 0, s[52:53]
	global_load_dword v36, v[12:13], off nt
	v_lshl_add_u64 v[12:13], v[12:13], 0, s[52:53]
	global_load_dword v37, v[12:13], off nt
	v_lshl_add_u64 v[12:13], v[12:13], 0, s[52:53]
	global_load_dword v38, v[12:13], off nt
	v_lshl_add_u64 v[12:13], v[12:13], 0, s[52:53]
	global_load_dword v39, v[12:13], off nt
	s_add_i32 s47, s46, 3
	s_cmp_lt_u32 s47, 0x2600
	s_cbranch_scc0 .Lcva_p_l3_m1
	s_sub_i32 s54, s47, 0x1e00
	s_lshr_b32 s55, s54, 6
	s_lshl_b32 s55, s55, 6
	s_and_b32 s54, s54, 63
	s_lshl_b32 s54, s54, 6
	s_mov_b32 s52, 0x2000
	s_cmpk_lt_u32 s54, 0x400
	s_cbranch_scc0 .Lcva_p_l3_k1
	v_readlane_b32 s48, v251, 6
	v_readlane_b32 s49, v251, 7
	s_mov_b32 s60, s54
	s_branch .Lcva_p_l3_k3

; __device__ __forceinline__ unsigned cvt_pk(float lo, float hi) { const f32x2 v = {lo, hi}; const bf16x2_t b = __builtin_convertvector(v, bf16x2_t); return __builtin_bit_cast(unsigned, b); }
; template <int NT> __device__ __forceinline__ void conv_tilesN(const Params& p, LAS unsigned char* lds, int tid, int t0, int stride, int t_end) {
;     ...
;         int loc, ktn, ldd; size_t dsto;
;         if (t < 7680) { loc = t; ktn = 32; ldd = 2048; dsto = WS_WIN; }
;         else if (t < 9728) { loc = t - 7680; ktn = 64; ldd = 4096; dsto = WS_WCAT; }
;         else if (t < 10752) { loc = t - 9728; ktn = 32; ldd = 2048; dsto = WS_WOUT; }
;         else if (t < 16384) { loc = t - 10752; ktn = 32; ldd = 2048; dsto = WS_WGU; }
;         else if (t < 19200) { loc = t - 16384; ktn = 88; ldd = 5632; dsto = WS_WDN; }
;         else { loc = t - 19200; ktn = 32; ldd = 2048; dsto = WS_WMKV; }
;         const int n0 = (loc / ktn) * 64, k0 = (loc % ktn) * 64;
;         __syncthreads();
; #pragma unroll
;         for (int r = 0; r < 8; ++r) tile[(ty * 8 + r) * 65 + tx] = v[q][r];
;         __syncthreads();
;         const int nn = tid >> 3, kc = (tid & 7) * 8;
;         float w[8];
; #pragma unroll
;         for (int e = 0; e < 8; ++e) w[e] = tile[(kc + e) * 65 + nn];
;         u32x4 o; o[0] = cvt_pk(w[0], w[1]); o[1] = cvt_pk(w[2], w[3]); o[2] = cvt_pk(w[4], w[5]); o[3] = cvt_pk(w[6], w[7]);
;         *(u32x4*)((bf16_t*)(ws + dsto) + (size_t)(n0 + nn) * ldd + k0 + kc) = o;
; __device__ __forceinline__ void conv_queue(const Params& p, LAS unsigned char* lds, unsigned* ctr, int t_begin, int t_end) {
;     ...
;     __syncthreads();
;     if (tid == 0) *slot = nxt;
;     __syncthreads();
;     const int base = t_begin + (int)__builtin_amdgcn_readfirstlane(*slot);
;     if (base >= t_end) break;
;     if (tid == 0) nxt = atomicAdd(ctr, 4u);
.Lcva_v0x_w:
	s_mov_b64 exec, s[40:41]
	s_waitcnt lgkmcnt(0)
	s_barrier
	ds_read_b32 v11, v8
	s_waitcnt lgkmcnt(0)
	s_nop 0
	v_readfirstlane_b32 s63, v11
	s_nop 1
	s_add_i32 s63, s63, 0x1e00
	s_and_saveexec_b64 s[40:41], s[44:45]
	s_cbranch_execz .Lcva_v0f_a
	global_atomic_add v10, v65, v9, s[24:25] offset:16 sc0
.Lcva_v0f_a:
	s_mov_b64 exec, s[40:41]
	s_add_i32 s47, s46, 0
	s_cmp_lt_u32 s47, 0x2600
	s_cbranch_scc0 .Lcva_v0_t_s0_m1
	s_sub_i32 s54, s47, 0x1e00
	s_lshr_b32 s55, s54, 6
	s_lshl_b32 s55, s55, 6
	s_and_b32 s54, s54, 63
	s_lshl_b32 s54, s54, 6
	s_mov_b32 s58, 0x2000
	s_mul_i32 s60, s55, 0x2000
	s_lshl_b32 s61, s54, 1
	s_add_i32 s60, s60, s61
	s_add_u32 s56, s24, 0x6109000
	s_addc_u32 s57, s25, 0
	s_add_u32 s56, s56, s60
	s_addc_u32 s57, s57, 0
	v_mad_u32_u24 v14, v3, s58, v4
	s_branch .Lcva_v0_t_s0_dd
.Lcva_v0_t_s0_m1:
	s_cmp_lt_u32 s47, 0x2a00
	s_cbranch_scc0 .Lcva_v0_t_s0_m2
	s_sub_i32 s54, s47, 0x2600
	s_lshr_b32 s55, s54, 5
	s_lshl_b32 s55, s55, 6
	s_and_b32 s54, s54, 31
	s_lshl_b32 s54, s54, 6
	s_mov_b32 s58, 0x1000
	s_mul_i32 s60, s55, 0x1000
	s_lshl_b32 s61, s54, 1
	s_add_i32 s60, s60, s61
	s_add_u32 s56, s24, 0x7109000
	s_addc_u32 s57, s25, 0
	s_add_u32 s56, s56, s60
	s_addc_u32 s57, s57, 0
	v_mad_u32_u24 v14, v3, s58, v4
	s_branch .Lcva_v0_t_s0_dd
.Lcva_v0_t_s0_m2:
	s_sub_i32 s54, s47, 0x2a00
	s_lshr_b32 s55, s54, 5
	s_mov_b32 s59, s55
	s_lshl_b32 s55, s55, 6
	s_and_b32 s54, s54, 31
	s_lshl_b32 s54, s54, 6
	s_mov_b32 s58, 0x1000
	s_mul_i32 s60, s55, 0x1000
	s_lshl_b32 s61, s54, 1
	s_add_i32 s60, s60, s61
	s_add_u32 s56, s24, 0x7909000
	s_addc_u32 s57, s25, 0
	s_add_u32 s56, s56, s60
	s_addc_u32 s57, s57, 0
	v_mad_u32_u24 v14, v3, s58, v4
.Lcva_v0_t_s0_dd:
	s_waitcnt vmcnt(24)
	ds_write_b32 v5, v16
	ds_write_b32 v5, v17 offset:260
	ds_write_b32 v5, v18 offset:520
	ds_write_b32 v5, v19 offset:780
	ds_write_b32 v5, v20 offset:1040
	ds_write_b32 v5, v21 offset:1300
	ds_write_b32 v5, v22 offset:1560
	ds_write_b32 v5, v23 offset:1820
	s_waitcnt lgkmcnt(0)
	s_barrier
	ds_read_b32 v48, v6
	ds_read_b32 v49, v6 offset:260
	ds_read_b32 v50, v6 offset:520
	ds_read_b32 v51, v6 offset:780
	ds_read_b32 v52, v6 offset:1040
	ds_read_b32 v53, v6 offset:1300
	ds_read_b32 v54, v6 offset:1560
	ds_read_b32 v55, v6 offset:1820
	s_waitcnt lgkmcnt(0)
	v_cvt_pk_bf16_f32 v56, v48, v49
	v_cvt_pk_bf16_f32 v57, v50, v51
	v_cvt_pk_bf16_f32 v58, v52, v53
	v_cvt_pk_bf16_f32 v59, v54, v55
	global_store_dwordx4 v14, v[56:59], s[56:57]
	s_cmp_ge_i32 s63, 0x4000
	s_cbranch_scc1 .Lcva_v0_last
	s_add_i32 s47, s63, 0
	s_cmp_lt_u32 s47, 0x2600
	s_cbranch_scc0 .Lcva_v0_n_l0_m1
	s_sub_i32 s54, s47, 0x1e00
	s_lshr_b32 s55, s54, 6
	s_lshl_b32 s55, s55, 6
	s_and_b32 s54, s54, 63
	s_lshl_b32 s54, s54, 6
	s_mov_b32 s52, 0x2000
	s_cmpk_lt_u32 s54, 0x400
	s_cbranch_scc0 .Lcva_v0_n_l0_k1
	v_readlane_b32 s48, v251, 6
	v_readlane_b32 s49, v251, 7
	s_mov_b32 s60, s54
	s_branch .Lcva_v0_n_l0_k3

; template <int NT> __device__ __forceinline__ void conv_tilesN(const Params& p, LAS unsigned char* lds, int tid, int t0, int stride, int t_end) {
;     ...
;         int mat, loc, ktn;
;         if (t < 7680) { mat = 0; loc = t; ktn = 32; }
;         else if (t < 9728) { mat = 1; loc = t - 7680; ktn = 64; }
;         else if (t < 10752) { mat = 2; loc = t - 9728; ktn = 32; }
;         else if (t < 16384) { mat = 3; loc = t - 10752; ktn = 32; }
;         else if (t < 19200) { mat = 4; loc = t - 16384; ktn = 88; }
;         else { mat = 5; loc = t - 19200; ktn = 32; }
;         const int n0 = (loc / ktn) * 64, k0 = (loc % ktn) * 64;
;         const int n = n0 + tx;
;         const float* ptr; int ld, col, kk0 = k0;
;         if (mat == 0) {
;           ptr = p.in[6]; ld = INW; col = n;
;           if (n >= OFF_RQ && n < OFF_RV) { const int s = n & 127; col = (n & ~127) + ((s >> 4) & 1) * 64 + (s >> 5) * 16 + (s & 15); }
;         } else if (mat == 1) {
;           ld = 2048; col = n;
;           if (k0 < 1024) { ptr = p.in[11]; } else if (k0 < 3072) { ptr = p.in[13]; kk0 = k0 - 1024; } else { ptr = p.in[16]; kk0 = k0 - 3072; }
;         } else if (mat == 2) { ptr = p.in[17]; ld = 2048; col = n; }
;         else if (mat == 3) {
;           const int T = n >> 8, s = n & 255;
;           const int f = 128 * T + 64 * (s >> 7) + 16 * ((s >> 5) & 3) + (s & 15);
;           ptr = ((s >> 4) & 1) ? p.in[21] : p.in[20]; ld = DFF; col = f;
;         } else if (mat == 4) { ptr = p.in[22]; ld = 2048; col = n; }
;         else { if (n < 1024) { ptr = p.in[14]; col = n; } else { ptr = p.in[15]; col = n - 1024; } ld = 1024; }
;         const float* s0 = ptr + (size_t)(kk0 + ty * 8) * ld + col;
; #pragma unroll
;         for (int r = 0; r < 8; ++r) v[q][r] = __builtin_nontemporal_load(s0 + (size_t)r * ld);
.Lcva_v0_n_l0_dd:
	global_load_dword v68, v[12:13], off nt
	v_lshl_add_u64 v[12:13], v[12:13], 0, s[52:53]
	global_load_dword v69, v[12:13], off nt
	v_lshl_add_u64 v[12:13], v[12:13], 0, s[52:53]
	global_load_dword v70, v[12:13], off nt
	v_lshl_add_u64 v[12:13], v[12:13], 0, s[52:53]
	global_load_dword v71, v[12:13], off nt
	v_lshl_add_u64 v[12:13], v[12:13], 0, s[52:53]
	global_load_dword v72, v[12:13], off nt
	v_lshl_add_u64 v[12:13], v[12:13], 0, s[52:53]
	global_load_dword v73, v[12:13], off nt
	v_lshl_add_u64 v[12:13], v[12:13], 0, s[52:53]
	global_load_dword v74, v[12:13], off nt
	v_lshl_add_u64 v[12:13], v[12:13], 0, s[52:53]
	global_load_dword v75, v[12:13], off nt
	s_add_i32 s47, s63, 1
	s_cmp_lt_u32 s47, 0x2600
	s_cbranch_scc0 .Lcva_v0_n_l1_m1
	s_sub_i32 s54, s47, 0x1e00
	s_lshr_b32 s55, s54, 6
	s_lshl_b32 s55, s55, 6
	s_and_b32 s54, s54, 63
	s_lshl_b32 s54, s54, 6
	s_mov_b32 s52, 0x2000
	s_cmpk_lt_u32 s54, 0x400
	s_cbranch_scc0 .Lcva_v0_n_l1_k1
	v_readlane_b32 s48, v251, 6
	v_readlane_b32 s49, v251, 7
	s_mov_b32 s60, s54
	s_branch .Lcva_v0_n_l1_k3

; template <int NT> __device__ __forceinline__ void conv_tilesN(const Params& p, LAS unsigned char* lds, int tid, int t0, int stride, int t_end) {
;     ...
;         int mat, loc, ktn;
;         if (t < 7680) { mat = 0; loc = t; ktn = 32; }
;         else if (t < 9728) { mat = 1; loc = t - 7680; ktn = 64; }
;         else if (t < 10752) { mat = 2; loc = t - 9728; ktn = 32; }
;         else if (t < 16384) { mat = 3; loc = t - 10752; ktn = 32; }
;         else if (t < 19200) { mat = 4; loc = t - 16384; ktn = 88; }
;         else { mat = 5; loc = t - 19200; ktn = 32; }
;         const int n0 = (loc / ktn) * 64, k0 = (loc % ktn) * 64;
;         const int n = n0 + tx;
;         const float* ptr; int ld, col, kk0 = k0;
;         if (mat == 0) {
;           ptr = p.in[6]; ld = INW; col = n;
;           if (n >= OFF_RQ && n < OFF_RV) { const int s = n & 127; col = (n & ~127) + ((s >> 4) & 1) * 64 + (s >> 5) * 16 + (s & 15); }
;         } else if (mat == 1) {
;           ld = 2048; col = n;
;           if (k0 < 1024) { ptr = p.in[11]; } else if (k0 < 3072) { ptr = p.in[13]; kk0 = k0 - 1024; } else { ptr = p.in[16]; kk0 = k0 - 3072; }
;         } else if (mat == 2) { ptr = p.in[17]; ld = 2048; col = n; }
;         else if (mat == 3) {
;           const int T = n >> 8, s = n & 255;
;           const int f = 128 * T + 64 * (s >> 7) + 16 * ((s >> 5) & 3) + (s & 15);
;           ptr = ((s >> 4) & 1) ? p.in[21] : p.in[20]; ld = DFF; col = f;
;         } else if (mat == 4) { ptr = p.in[22]; ld = 2048; col = n; }
;         else { if (n < 1024) { ptr = p.in[14]; col = n; } else { ptr = p.in[15]; col = n - 1024; } ld = 1024; }
;         const float* s0 = ptr + (size_t)(kk0 + ty * 8) * ld + col;
; #pragma unroll
;         for (int r = 0; r < 8; ++r) v[q][r] = __builtin_nontemporal_load(s0 + (size_t)r * ld);
.Lcva_v0_n_l1_dd:
	global_load_dword v76, v[12:13], off nt
	v_lshl_add_u64 v[12:13], v[12:13], 0, s[52:53]
	global_load_dword v77, v[12:13], off nt
	v_lshl_add_u64 v[12:13], v[12:13], 0, s[52:53]
	global_load_dword v78, v[12:13], off nt
	v_lshl_add_u64 v[12:13], v[12:13], 0, s[52:53]
	global_load_dword v79, v[12:13], off nt
	v_lshl_add_u64 v[12:13], v[12:13], 0, s[52:53]
	global_load_dword v80, v[12:13], off nt
	v_lshl_add_u64 v[12:13], v[12:13], 0, s[52:53]
	global_load_dword v81, v[12:13], off nt
	v_lshl_add_u64 v[12:13], v[12:13], 0, s[52:53]
	global_load_dword v82, v[12:13], off nt
	v_lshl_add_u64 v[12:13], v[12:13], 0, s[52:53]
	global_load_dword v83, v[12:13], off nt
	s_add_i32 s47, s63, 2
	s_cmp_lt_u32 s47, 0x2600
	s_cbranch_scc0 .Lcva_v0_n_l2_m1
	s_sub_i32 s54, s47, 0x1e00
	s_lshr_b32 s55, s54, 6
	s_lshl_b32 s55, s55, 6
	s_and_b32 s54, s54, 63
	s_lshl_b32 s54, s54, 6
	s_mov_b32 s52, 0x2000
	s_cmpk_lt_u32 s54, 0x400
	s_cbranch_scc0 .Lcva_v0_n_l2_k1
	v_readlane_b32 s48, v251, 6
	v_readlane_b32 s49, v251, 7
	s_mov_b32 s60, s54
	s_branch .Lcva_v0_n_l2_k3

; template <int NT> __device__ __forceinline__ void conv_tilesN(const Params& p, LAS unsigned char* lds, int tid, int t0, int stride, int t_end) {
;     ...
;         int mat, loc, ktn;
;         if (t < 7680) { mat = 0; loc = t; ktn = 32; }
;         else if (t < 9728) { mat = 1; loc = t - 7680; ktn = 64; }
;         else if (t < 10752) { mat = 2; loc = t - 9728; ktn = 32; }
;         else if (t < 16384) { mat = 3; loc = t - 10752; ktn = 32; }
;         else if (t < 19200) { mat = 4; loc = t - 16384; ktn = 88; }
;         else { mat = 5; loc = t - 19200; ktn = 32; }
;         const int n0 = (loc / ktn) * 64, k0 = (loc % ktn) * 64;
;         const int n = n0 + tx;
;         const float* ptr; int ld, col, kk0 = k0;
;         if (mat == 0) {
;           ptr = p.in[6]; ld = INW; col = n;
;           if (n >= OFF_RQ && n < OFF_RV) { const int s = n & 127; col = (n & ~127) + ((s >> 4) & 1) * 64 + (s >> 5) * 16 + (s & 15); }
;         } else if (mat == 1) {
;           ld = 2048; col = n;
;           if (k0 < 1024) { ptr = p.in[11]; } else if (k0 < 3072) { ptr = p.in[13]; kk0 = k0 - 1024; } else { ptr = p.in[16]; kk0 = k0 - 3072; }
;         } else if (mat == 2) { ptr = p.in[17]; ld = 2048; col = n; }
;         else if (mat == 3) {
;           const int T = n >> 8, s = n & 255;
;           const int f = 128 * T + 64 * (s >> 7) + 16 * ((s >> 5) & 3) + (s & 15);
;           ptr = ((s >> 4) & 1) ? p.in[21] : p.in[20]; ld = DFF; col = f;
;         } else if (mat == 4) { ptr = p.in[22]; ld = 2048; col = n; }
;         else { if (n < 1024) { ptr = p.in[14]; col = n; } else { ptr = p.in[15]; col = n - 1024; } ld = 1024; }
;         const float* s0 = ptr + (size_t)(kk0 + ty * 8) * ld + col;
; #pragma unroll
;         for (int r = 0; r < 8; ++r) v[q][r] = __builtin_nontemporal_load(s0 + (size_t)r * ld);
.Lcva_v0_n_l2_dd:
	global_load_dword v84, v[12:13], off nt
	v_lshl_add_u64 v[12:13], v[12:13], 0, s[52:53]
	global_load_dword v85, v[12:13], off nt
	v_lshl_add_u64 v[12:13], v[12:13], 0, s[52:53]
	global_load_dword v86, v[12:13], off nt
	v_lshl_add_u64 v[12:13], v[12:13], 0, s[52:53]
	global_load_dword v87, v[12:13], off nt
	v_lshl_add_u64 v[12:13], v[12:13], 0, s[52:53]
	global_load_dword v88, v[12:13], off nt
	v_lshl_add_u64 v[12:13], v[12:13], 0, s[52:53]
	global_load_dword v89, v[12:13], off nt
	v_lshl_add_u64 v[12:13], v[12:13], 0, s[52:53]
	global_load_dword v90, v[12:13], off nt
	v_lshl_add_u64 v[12:13], v[12:13], 0, s[52:53]
	global_load_dword v91, v[12:13], off nt
	s_add_i32 s47, s63, 3
	s_cmp_lt_u32 s47, 0x2600
	s_cbranch_scc0 .Lcva_v0_n_l3_m1
	s_sub_i32 s54, s47, 0x1e00
	s_lshr_b32 s55, s54, 6
	s_lshl_b32 s55, s55, 6
	s_and_b32 s54, s54, 63
	s_lshl_b32 s54, s54, 6
	s_mov_b32 s52, 0x2000
	s_cmpk_lt_u32 s54, 0x400
	s_cbranch_scc0 .Lcva_v0_n_l3_k1
	v_readlane_b32 s48, v251, 6
	v_readlane_b32 s49, v251, 7
	s_mov_b32 s60, s54
	s_branch .Lcva_v0_n_l3_k3

; template <int NT> __device__ __forceinline__ void conv_tilesN(const Params& p, LAS unsigned char* lds, int tid, int t0, int stride, int t_end) {
;     ...
;         const float* s0 = ptr + (size_t)(kk0 + ty * 8) * ld + col;
; #pragma unroll
;         for (int r = 0; r < 8; ++r) v[q][r] = __builtin_nontemporal_load(s0 + (size_t)r * ld);
;       }
;     }
; #pragma unroll
;     for (int q = 0; q < NT; ++q) {
;       const int t = t0 + q * stride;
;       if (t < t_end) {
;         int loc, ktn, ldd; size_t dsto;
;         if (t < 7680) { loc = t; ktn = 32; ldd = 2048; dsto = WS_WIN; }
;         else if (t < 9728) { loc = t - 7680; ktn = 64; ldd = 4096; dsto = WS_WCAT; }
;         else if (t < 10752) { loc = t - 9728; ktn = 32; ldd = 2048; dsto = WS_WOUT; }
;         else if (t < 16384) { loc = t - 10752; ktn = 32; ldd = 2048; dsto = WS_WGU; }
;         else if (t < 19200) { loc = t - 16384; ktn = 88; ldd = 5632; dsto = WS_WDN; }
;         else { loc = t - 19200; ktn = 32; ldd = 2048; dsto = WS_WMKV; }
;         const int n0 = (loc / ktn) * 64, k0 = (loc % ktn) * 64;
.Lcva_v0_n_l3_dd:
	global_load_dword v92, v[12:13], off nt
	v_lshl_add_u64 v[12:13], v[12:13], 0, s[52:53]
	global_load_dword v93, v[12:13], off nt
	v_lshl_add_u64 v[12:13], v[12:13], 0, s[52:53]
	global_load_dword v94, v[12:13], off nt
	v_lshl_add_u64 v[12:13], v[12:13], 0, s[52:53]
	global_load_dword v95, v[12:13], off nt
	v_lshl_add_u64 v[12:13], v[12:13], 0, s[52:53]
	global_load_dword v96, v[12:13], off nt
	v_lshl_add_u64 v[12:13], v[12:13], 0, s[52:53]
	global_load_dword v97, v[12:13], off nt
	v_lshl_add_u64 v[12:13], v[12:13], 0, s[52:53]
	global_load_dword v98, v[12:13], off nt
	v_lshl_add_u64 v[12:13], v[12:13], 0, s[52:53]
	global_load_dword v99, v[12:13], off nt
	s_add_i32 s47, s46, 1
	s_cmp_lt_u32 s47, 0x2600
	s_cbranch_scc0 .Lcva_v0_a_s1_m1
	s_sub_i32 s54, s47, 0x1e00
	s_lshr_b32 s55, s54, 6
	s_lshl_b32 s55, s55, 6
	s_and_b32 s54, s54, 63
	s_lshl_b32 s54, s54, 6
	s_mov_b32 s58, 0x2000
	s_mul_i32 s60, s55, 0x2000
	s_lshl_b32 s61, s54, 1
	s_add_i32 s60, s60, s61
	s_add_u32 s56, s24, 0x6109000
	s_addc_u32 s57, s25, 0
	s_add_u32 s56, s56, s60
	s_addc_u32 s57, s57, 0
	v_mad_u32_u24 v14, v3, s58, v4
	s_branch .Lcva_v0_a_s1_dd

; __device__ __forceinline__ unsigned cvt_pk(float lo, float hi) { const f32x2 v = {lo, hi}; const bf16x2_t b = __builtin_convertvector(v, bf16x2_t); return __builtin_bit_cast(unsigned, b); }
; template <int NT> __device__ __forceinline__ void conv_tilesN(const Params& p, LAS unsigned char* lds, int tid, int t0, int stride, int t_end) {
;     ...
;         int loc, ktn, ldd; size_t dsto;
;         if (t < 7680) { loc = t; ktn = 32; ldd = 2048; dsto = WS_WIN; }
;         else if (t < 9728) { loc = t - 7680; ktn = 64; ldd = 4096; dsto = WS_WCAT; }
;         else if (t < 10752) { loc = t - 9728; ktn = 32; ldd = 2048; dsto = WS_WOUT; }
;         else if (t < 16384) { loc = t - 10752; ktn = 32; ldd = 2048; dsto = WS_WGU; }
;         else if (t < 19200) { loc = t - 16384; ktn = 88; ldd = 5632; dsto = WS_WDN; }
;         else { loc = t - 19200; ktn = 32; ldd = 2048; dsto = WS_WMKV; }
;         const int n0 = (loc / ktn) * 64, k0 = (loc % ktn) * 64;
;         __syncthreads();
; #pragma unroll
;         for (int r = 0; r < 8; ++r) tile[(ty * 8 + r) * 65 + tx] = v[q][r];
;         __syncthreads();
;         const int nn = tid >> 3, kc = (tid & 7) * 8;
;         float w[8];
; #pragma unroll
;         for (int e = 0; e < 8; ++e) w[e] = tile[(kc + e) * 65 + nn];
;         u32x4 o; o[0] = cvt_pk(w[0], w[1]); o[1] = cvt_pk(w[2], w[3]); o[2] = cvt_pk(w[4], w[5]); o[3] = cvt_pk(w[6], w[7]);
;         *(u32x4*)((bf16_t*)(ws + dsto) + (size_t)(n0 + nn) * ldd + k0 + kc) = o;
.Lcva_v0_a_s1_dd:
	s_barrier
	s_waitcnt vmcnt(48)
	ds_write_b32 v5, v24
	ds_write_b32 v5, v25 offset:260
	ds_write_b32 v5, v26 offset:520
	ds_write_b32 v5, v27 offset:780
	ds_write_b32 v5, v28 offset:1040
	ds_write_b32 v5, v29 offset:1300
	ds_write_b32 v5, v30 offset:1560
	ds_write_b32 v5, v31 offset:1820
	s_waitcnt lgkmcnt(0)
	s_barrier
	ds_read_b32 v48, v6
	ds_read_b32 v49, v6 offset:260
	ds_read_b32 v50, v6 offset:520
	ds_read_b32 v51, v6 offset:780
	ds_read_b32 v52, v6 offset:1040
	ds_read_b32 v53, v6 offset:1300
	ds_read_b32 v54, v6 offset:1560
	ds_read_b32 v55, v6 offset:1820
	s_waitcnt lgkmcnt(0)
	v_cvt_pk_bf16_f32 v56, v48, v49
	v_cvt_pk_bf16_f32 v57, v50, v51
	v_cvt_pk_bf16_f32 v58, v52, v53
	v_cvt_pk_bf16_f32 v59, v54, v55
	global_store_dwordx4 v14, v[56:59], s[56:57]
	s_add_i32 s47, s46, 2
	s_cmp_lt_u32 s47, 0x2600
	s_cbranch_scc0 .Lcva_v0_a_s2_m1
	s_sub_i32 s54, s47, 0x1e00
	s_lshr_b32 s55, s54, 6
	s_lshl_b32 s55, s55, 6
	s_and_b32 s54, s54, 63
	s_lshl_b32 s54, s54, 6
	s_mov_b32 s58, 0x2000
	s_mul_i32 s60, s55, 0x2000
	s_lshl_b32 s61, s54, 1
	s_add_i32 s60, s60, s61
	s_add_u32 s56, s24, 0x6109000
	s_addc_u32 s57, s25, 0
	s_add_u32 s56, s56, s60
	s_addc_u32 s57, s57, 0
	v_mad_u32_u24 v14, v3, s58, v4
	s_branch .Lcva_v0_a_s2_dd

; __device__ __forceinline__ unsigned cvt_pk(float lo, float hi) { const f32x2 v = {lo, hi}; const bf16x2_t b = __builtin_convertvector(v, bf16x2_t); return __builtin_bit_cast(unsigned, b); }
; template <int NT> __device__ __forceinline__ void conv_tilesN(const Params& p, LAS unsigned char* lds, int tid, int t0, int stride, int t_end) {
;     ...
;         int loc, ktn, ldd; size_t dsto;
;         if (t < 7680) { loc = t; ktn = 32; ldd = 2048; dsto = WS_WIN; }
;         else if (t < 9728) { loc = t - 7680; ktn = 64; ldd = 4096; dsto = WS_WCAT; }
;         else if (t < 10752) { loc = t - 9728; ktn = 32; ldd = 2048; dsto = WS_WOUT; }
;         else if (t < 16384) { loc = t - 10752; ktn = 32; ldd = 2048; dsto = WS_WGU; }
;         else if (t < 19200) { loc = t - 16384; ktn = 88; ldd = 5632; dsto = WS_WDN; }
;         else { loc = t - 19200; ktn = 32; ldd = 2048; dsto = WS_WMKV; }
;         const int n0 = (loc / ktn) * 64, k0 = (loc % ktn) * 64;
;         __syncthreads();
; #pragma unroll
;         for (int r = 0; r < 8; ++r) tile[(ty * 8 + r) * 65 + tx] = v[q][r];
;         __syncthreads();
;         const int nn = tid >> 3, kc = (tid & 7) * 8;
;         float w[8];
; #pragma unroll
;         for (int e = 0; e < 8; ++e) w[e] = tile[(kc + e) * 65 + nn];
;         u32x4 o; o[0] = cvt_pk(w[0], w[1]); o[1] = cvt_pk(w[2], w[3]); o[2] = cvt_pk(w[4], w[5]); o[3] = cvt_pk(w[6], w[7]);
;         *(u32x4*)((bf16_t*)(ws + dsto) + (size_t)(n0 + nn) * ldd + k0 + kc) = o;
.Lcva_v0_a_s2_dd:
	s_barrier
	s_waitcnt vmcnt(40)
	ds_write_b32 v5, v32
	ds_write_b32 v5, v33 offset:260
	ds_write_b32 v5, v34 offset:520
	ds_write_b32 v5, v35 offset:780
	ds_write_b32 v5, v36 offset:1040
	ds_write_b32 v5, v37 offset:1300
	ds_write_b32 v5, v38 offset:1560
	ds_write_b32 v5, v39 offset:1820
	s_waitcnt lgkmcnt(0)
	s_barrier
	ds_read_b32 v48, v6
	ds_read_b32 v49, v6 offset:260
	ds_read_b32 v50, v6 offset:520
	ds_read_b32 v51, v6 offset:780
	ds_read_b32 v52, v6 offset:1040
	ds_read_b32 v53, v6 offset:1300
	ds_read_b32 v54, v6 offset:1560
	ds_read_b32 v55, v6 offset:1820
	s_waitcnt lgkmcnt(0)
	v_cvt_pk_bf16_f32 v56, v48, v49
	v_cvt_pk_bf16_f32 v57, v50, v51
	v_cvt_pk_bf16_f32 v58, v52, v53
	v_cvt_pk_bf16_f32 v59, v54, v55
	global_store_dwordx4 v14, v[56:59], s[56:57]
	s_add_i32 s47, s46, 3
	s_cmp_lt_u32 s47, 0x2600
	s_cbranch_scc0 .Lcva_v0_a_s3_m1
	s_sub_i32 s54, s47, 0x1e00
	s_lshr_b32 s55, s54, 6
	s_lshl_b32 s55, s55, 6
	s_and_b32 s54, s54, 63
	s_lshl_b32 s54, s54, 6
	s_mov_b32 s58, 0x2000
	s_mul_i32 s60, s55, 0x2000
	s_lshl_b32 s61, s54, 1
	s_add_i32 s60, s60, s61
	s_add_u32 s56, s24, 0x6109000
	s_addc_u32 s57, s25, 0
	s_add_u32 s56, s56, s60
	s_addc_u32 s57, s57, 0
	v_mad_u32_u24 v14, v3, s58, v4
	s_branch .Lcva_v0_a_s3_dd

; template <int NT> __device__ __forceinline__ void conv_tilesN(const Params& p, LAS unsigned char* lds, int tid, int t0, int stride, int t_end) {
;     ...
;         int loc, ktn, ldd; size_t dsto;
;         if (t < 7680) { loc = t; ktn = 32; ldd = 2048; dsto = WS_WIN; }
;         else if (t < 9728) { loc = t - 7680; ktn = 64; ldd = 4096; dsto = WS_WCAT; }
;         else if (t < 10752) { loc = t - 9728; ktn = 32; ldd = 2048; dsto = WS_WOUT; }
;         else if (t < 16384) { loc = t - 10752; ktn = 32; ldd = 2048; dsto = WS_WGU; }
;         else if (t < 19200) { loc = t - 16384; ktn = 88; ldd = 5632; dsto = WS_WDN; }
;         else { loc = t - 19200; ktn = 32; ldd = 2048; dsto = WS_WMKV; }
;         const int n0 = (loc / ktn) * 64, k0 = (loc % ktn) * 64;
.Lcva_v0_last:
	s_add_i32 s47, s46, 1
	s_cmp_lt_u32 s47, 0x2600
	s_cbranch_scc0 .Lcva_v0_b_s1_m1
	s_sub_i32 s54, s47, 0x1e00
	s_lshr_b32 s55, s54, 6
	s_lshl_b32 s55, s55, 6
	s_and_b32 s54, s54, 63
	s_lshl_b32 s54, s54, 6
	s_mov_b32 s58, 0x2000
	s_mul_i32 s60, s55, 0x2000
	s_lshl_b32 s61, s54, 1
	s_add_i32 s60, s60, s61
	s_add_u32 s56, s24, 0x6109000
	s_addc_u32 s57, s25, 0
	s_add_u32 s56, s56, s60
	s_addc_u32 s57, s57, 0
	v_mad_u32_u24 v14, v3, s58, v4
	s_branch .Lcva_v0_b_s1_dd

; __device__ __forceinline__ unsigned cvt_pk(float lo, float hi) { const f32x2 v = {lo, hi}; const bf16x2_t b = __builtin_convertvector(v, bf16x2_t); return __builtin_bit_cast(unsigned, b); }
; template <int NT> __device__ __forceinline__ void conv_tilesN(const Params& p, LAS unsigned char* lds, int tid, int t0, int stride, int t_end) {
;     ...
;         int loc, ktn, ldd; size_t dsto;
;         if (t < 7680) { loc = t; ktn = 32; ldd = 2048; dsto = WS_WIN; }
;         else if (t < 9728) { loc = t - 7680; ktn = 64; ldd = 4096; dsto = WS_WCAT; }
;         else if (t < 10752) { loc = t - 9728; ktn = 32; ldd = 2048; dsto = WS_WOUT; }
;         else if (t < 16384) { loc = t - 10752; ktn = 32; ldd = 2048; dsto = WS_WGU; }
;         else if (t < 19200) { loc = t - 16384; ktn = 88; ldd = 5632; dsto = WS_WDN; }
;         else { loc = t - 19200; ktn = 32; ldd = 2048; dsto = WS_WMKV; }
;         const int n0 = (loc / ktn) * 64, k0 = (loc % ktn) * 64;
;         __syncthreads();
; #pragma unroll
;         for (int r = 0; r < 8; ++r) tile[(ty * 8 + r) * 65 + tx] = v[q][r];
;         __syncthreads();
;         const int nn = tid >> 3, kc = (tid & 7) * 8;
;         float w[8];
; #pragma unroll
;         for (int e = 0; e < 8; ++e) w[e] = tile[(kc + e) * 65 + nn];
;         u32x4 o; o[0] = cvt_pk(w[0], w[1]); o[1] = cvt_pk(w[2], w[3]); o[2] = cvt_pk(w[4], w[5]); o[3] = cvt_pk(w[6], w[7]);
;         *(u32x4*)((bf16_t*)(ws + dsto) + (size_t)(n0 + nn) * ldd + k0 + kc) = o;
.Lcva_v0_b_s1_dd:
	s_barrier
	s_waitcnt vmcnt(16)
	ds_write_b32 v5, v24
	ds_write_b32 v5, v25 offset:260
	ds_write_b32 v5, v26 offset:520
	ds_write_b32 v5, v27 offset:780
	ds_write_b32 v5, v28 offset:1040
	ds_write_b32 v5, v29 offset:1300
	ds_write_b32 v5, v30 offset:1560
	ds_write_b32 v5, v31 offset:1820
	s_waitcnt lgkmcnt(0)
	s_barrier
	ds_read_b32 v48, v6
	ds_read_b32 v49, v6 offset:260
	ds_read_b32 v50, v6 offset:520
	ds_read_b32 v51, v6 offset:780
	ds_read_b32 v52, v6 offset:1040
	ds_read_b32 v53, v6 offset:1300
	ds_read_b32 v54, v6 offset:1560
	ds_read_b32 v55, v6 offset:1820
	s_waitcnt lgkmcnt(0)
	v_cvt_pk_bf16_f32 v56, v48, v49
	v_cvt_pk_bf16_f32 v57, v50, v51
	v_cvt_pk_bf16_f32 v58, v52, v53
	v_cvt_pk_bf16_f32 v59, v54, v55
	global_store_dwordx4 v14, v[56:59], s[56:57]
	s_add_i32 s47, s46, 2
	s_cmp_lt_u32 s47, 0x2600
	s_cbranch_scc0 .Lcva_v0_b_s2_m1
	s_sub_i32 s54, s47, 0x1e00
	s_lshr_b32 s55, s54, 6
	s_lshl_b32 s55, s55, 6
	s_and_b32 s54, s54, 63
	s_lshl_b32 s54, s54, 6
	s_mov_b32 s58, 0x2000
	s_mul_i32 s60, s55, 0x2000
	s_lshl_b32 s61, s54, 1
	s_add_i32 s60, s60, s61
	s_add_u32 s56, s24, 0x6109000
	s_addc_u32 s57, s25, 0
	s_add_u32 s56, s56, s60
	s_addc_u32 s57, s57, 0
	v_mad_u32_u24 v14, v3, s58, v4
	s_branch .Lcva_v0_b_s2_dd

; __device__ __forceinline__ unsigned cvt_pk(float lo, float hi) { const f32x2 v = {lo, hi}; const bf16x2_t b = __builtin_convertvector(v, bf16x2_t); return __builtin_bit_cast(unsigned, b); }
; template <int NT> __device__ __forceinline__ void conv_tilesN(const Params& p, LAS unsigned char* lds, int tid, int t0, int stride, int t_end) {
;     ...
;         int loc, ktn, ldd; size_t dsto;
;         if (t < 7680) { loc = t; ktn = 32; ldd = 2048; dsto = WS_WIN; }
;         else if (t < 9728) { loc = t - 7680; ktn = 64; ldd = 4096; dsto = WS_WCAT; }
;         else if (t < 10752) { loc = t - 9728; ktn = 32; ldd = 2048; dsto = WS_WOUT; }
;         else if (t < 16384) { loc = t - 10752; ktn = 32; ldd = 2048; dsto = WS_WGU; }
;         else if (t < 19200) { loc = t - 16384; ktn = 88; ldd = 5632; dsto = WS_WDN; }
;         else { loc = t - 19200; ktn = 32; ldd = 2048; dsto = WS_WMKV; }
;         const int n0 = (loc / ktn) * 64, k0 = (loc % ktn) * 64;
;         __syncthreads();
; #pragma unroll
;         for (int r = 0; r < 8; ++r) tile[(ty * 8 + r) * 65 + tx] = v[q][r];
;         __syncthreads();
;         const int nn = tid >> 3, kc = (tid & 7) * 8;
;         float w[8];
; #pragma unroll
;         for (int e = 0; e < 8; ++e) w[e] = tile[(kc + e) * 65 + nn];
;         u32x4 o; o[0] = cvt_pk(w[0], w[1]); o[1] = cvt_pk(w[2], w[3]); o[2] = cvt_pk(w[4], w[5]); o[3] = cvt_pk(w[6], w[7]);
;         *(u32x4*)((bf16_t*)(ws + dsto) + (size_t)(n0 + nn) * ldd + k0 + kc) = o;
.Lcva_v0_b_s2_dd:
	s_barrier
	s_waitcnt vmcnt(8)
	ds_write_b32 v5, v32
	ds_write_b32 v5, v33 offset:260
	ds_write_b32 v5, v34 offset:520
	ds_write_b32 v5, v35 offset:780
	ds_write_b32 v5, v36 offset:1040
	ds_write_b32 v5, v37 offset:1300
	ds_write_b32 v5, v38 offset:1560
	ds_write_b32 v5, v39 offset:1820
	s_waitcnt lgkmcnt(0)
	s_barrier
	ds_read_b32 v48, v6
	ds_read_b32 v49, v6 offset:260
	ds_read_b32 v50, v6 offset:520
	ds_read_b32 v51, v6 offset:780
	ds_read_b32 v52, v6 offset:1040
	ds_read_b32 v53, v6 offset:1300
	ds_read_b32 v54, v6 offset:1560
	ds_read_b32 v55, v6 offset:1820
	s_waitcnt lgkmcnt(0)
	v_cvt_pk_bf16_f32 v56, v48, v49
	v_cvt_pk_bf16_f32 v57, v50, v51
	v_cvt_pk_bf16_f32 v58, v52, v53
	v_cvt_pk_bf16_f32 v59, v54, v55
	global_store_dwordx4 v14, v[56:59], s[56:57]
	s_add_i32 s47, s46, 3
	s_cmp_lt_u32 s47, 0x2600
	s_cbranch_scc0 .Lcva_v0_b_s3_m1
	s_sub_i32 s54, s47, 0x1e00
	s_lshr_b32 s55, s54, 6
	s_lshl_b32 s55, s55, 6
	s_and_b32 s54, s54, 63
	s_lshl_b32 s54, s54, 6
	s_mov_b32 s58, 0x2000
	s_mul_i32 s60, s55, 0x2000
	s_lshl_b32 s61, s54, 1
	s_add_i32 s60, s60, s61
	s_add_u32 s56, s24, 0x6109000
	s_addc_u32 s57, s25, 0
	s_add_u32 s56, s56, s60
	s_addc_u32 s57, s57, 0
	v_mad_u32_u24 v14, v3, s58, v4
	s_branch .Lcva_v0_b_s3_dd

; __device__ __forceinline__ unsigned cvt_pk(float lo, float hi) { const f32x2 v = {lo, hi}; const bf16x2_t b = __builtin_convertvector(v, bf16x2_t); return __builtin_bit_cast(unsigned, b); }
; template <int NT> __device__ __forceinline__ void conv_tilesN(const Params& p, LAS unsigned char* lds, int tid, int t0, int stride, int t_end) {
;     ...
;         int mat, loc, ktn;
;         if (t < 7680) { mat = 0; loc = t; ktn = 32; }
;         else if (t < 9728) { mat = 1; loc = t - 7680; ktn = 64; }
;         else if (t < 10752) { mat = 2; loc = t - 9728; ktn = 32; }
;         else if (t < 16384) { mat = 3; loc = t - 10752; ktn = 32; }
;         else if (t < 19200) { mat = 4; loc = t - 16384; ktn = 88; }
;         else { mat = 5; loc = t - 19200; ktn = 32; }
;         const int n0 = (loc / ktn) * 64, k0 = (loc % ktn) * 64;
;         const int n = n0 + tx;
;         const float* ptr; int ld, col, kk0 = k0;
;     ...
;         __syncthreads();
; #pragma unroll
;         for (int r = 0; r < 8; ++r) tile[(ty * 8 + r) * 65 + tx] = v[q][r];
;         __syncthreads();
;         const int nn = tid >> 3, kc = (tid & 7) * 8;
;         float w[8];
; #pragma unroll
;         for (int e = 0; e < 8; ++e) w[e] = tile[(kc + e) * 65 + nn];
;         u32x4 o; o[0] = cvt_pk(w[0], w[1]); o[1] = cvt_pk(w[2], w[3]); o[2] = cvt_pk(w[4], w[5]); o[3] = cvt_pk(w[6], w[7]);
;         *(u32x4*)((bf16_t*)(ws + dsto) + (size_t)(n0 + nn) * ldd + k0 + kc) = o;
.Lcva_v1_t_s0_dd:
	s_waitcnt vmcnt(24)
	ds_write_b32 v5, v68
	ds_write_b32 v5, v69 offset:260
	ds_write_b32 v5, v70 offset:520
	ds_write_b32 v5, v71 offset:780
	ds_write_b32 v5, v72 offset:1040
	ds_write_b32 v5, v73 offset:1300
	ds_write_b32 v5, v74 offset:1560
	ds_write_b32 v5, v75 offset:1820
	s_waitcnt lgkmcnt(0)
	s_barrier
	ds_read_b32 v48, v6
	ds_read_b32 v49, v6 offset:260
	ds_read_b32 v50, v6 offset:520
	ds_read_b32 v51, v6 offset:780
	ds_read_b32 v52, v6 offset:1040
	ds_read_b32 v53, v6 offset:1300
	ds_read_b32 v54, v6 offset:1560
	ds_read_b32 v55, v6 offset:1820
	s_waitcnt lgkmcnt(0)
	v_cvt_pk_bf16_f32 v56, v48, v49
	v_cvt_pk_bf16_f32 v57, v50, v51
	v_cvt_pk_bf16_f32 v58, v52, v53
	v_cvt_pk_bf16_f32 v59, v54, v55
	global_store_dwordx4 v14, v[56:59], s[56:57]
	s_cmp_ge_i32 s63, 0x4000
	s_cbranch_scc1 .Lcva_v1_last
	s_add_i32 s47, s63, 0
	s_cmp_lt_u32 s47, 0x2600
	s_cbranch_scc0 .Lcva_v1_n_l0_m1
	s_sub_i32 s54, s47, 0x1e00
	s_lshr_b32 s55, s54, 6
	s_lshl_b32 s55, s55, 6
	s_and_b32 s54, s54, 63
	s_lshl_b32 s54, s54, 6
	s_mov_b32 s52, 0x2000
	s_cmpk_lt_u32 s54, 0x400
	s_cbranch_scc0 .Lcva_v1_n_l0_k1
	v_readlane_b32 s48, v251, 6
	v_readlane_b32 s49, v251, 7
	s_mov_b32 s60, s54
	s_branch .Lcva_v1_n_l0_k3

; template <int NT> __device__ __forceinline__ void conv_tilesN(const Params& p, LAS unsigned char* lds, int tid, int t0, int stride, int t_end) {
;     ...
;         int mat, loc, ktn;
;         if (t < 7680) { mat = 0; loc = t; ktn = 32; }
;         else if (t < 9728) { mat = 1; loc = t - 7680; ktn = 64; }
;         else if (t < 10752) { mat = 2; loc = t - 9728; ktn = 32; }
;         else if (t < 16384) { mat = 3; loc = t - 10752; ktn = 32; }
;         else if (t < 19200) { mat = 4; loc = t - 16384; ktn = 88; }
;         else { mat = 5; loc = t - 19200; ktn = 32; }
;         const int n0 = (loc / ktn) * 64, k0 = (loc % ktn) * 64;
;         const int n = n0 + tx;
;         const float* ptr; int ld, col, kk0 = k0;
;         if (mat == 0) {
;           ptr = p.in[6]; ld = INW; col = n;
;           if (n >= OFF_RQ && n < OFF_RV) { const int s = n & 127; col = (n & ~127) + ((s >> 4) & 1) * 64 + (s >> 5) * 16 + (s & 15); }
;         } else if (mat == 1) {
;           ld = 2048; col = n;
;           if (k0 < 1024) { ptr = p.in[11]; } else if (k0 < 3072) { ptr = p.in[13]; kk0 = k0 - 1024; } else { ptr = p.in[16]; kk0 = k0 - 3072; }
;         } else if (mat == 2) { ptr = p.in[17]; ld = 2048; col = n; }
;         else if (mat == 3) {
;           const int T = n >> 8, s = n & 255;
;           const int f = 128 * T + 64 * (s >> 7) + 16 * ((s >> 5) & 3) + (s & 15);
;           ptr = ((s >> 4) & 1) ? p.in[21] : p.in[20]; ld = DFF; col = f;
;         } else if (mat == 4) { ptr = p.in[22]; ld = 2048; col = n; }
;         else { if (n < 1024) { ptr = p.in[14]; col = n; } else { ptr = p.in[15]; col = n - 1024; } ld = 1024; }
;         const float* s0 = ptr + (size_t)(kk0 + ty * 8) * ld + col;
; #pragma unroll
;         for (int r = 0; r < 8; ++r) v[q][r] = __builtin_nontemporal_load(s0 + (size_t)r * ld);
.Lcva_v1_n_l0_dd:
	global_load_dword v16, v[12:13], off nt
	v_lshl_add_u64 v[12:13], v[12:13], 0, s[52:53]
	global_load_dword v17, v[12:13], off nt
	v_lshl_add_u64 v[12:13], v[12:13], 0, s[52:53]
	global_load_dword v18, v[12:13], off nt
	v_lshl_add_u64 v[12:13], v[12:13], 0, s[52:53]
	global_load_dword v19, v[12:13], off nt
	v_lshl_add_u64 v[12:13], v[12:13], 0, s[52:53]
	global_load_dword v20, v[12:13], off nt
	v_lshl_add_u64 v[12:13], v[12:13], 0, s[52:53]
	global_load_dword v21, v[12:13], off nt
	v_lshl_add_u64 v[12:13], v[12:13], 0, s[52:53]
	global_load_dword v22, v[12:13], off nt
	v_lshl_add_u64 v[12:13], v[12:13], 0, s[52:53]
	global_load_dword v23, v[12:13], off nt
	s_add_i32 s47, s63, 1
	s_cmp_lt_u32 s47, 0x2600
	s_cbranch_scc0 .Lcva_v1_n_l1_m1
	s_sub_i32 s54, s47, 0x1e00
	s_lshr_b32 s55, s54, 6
	s_lshl_b32 s55, s55, 6
	s_and_b32 s54, s54, 63
	s_lshl_b32 s54, s54, 6
	s_mov_b32 s52, 0x2000
	s_cmpk_lt_u32 s54, 0x400
	s_cbranch_scc0 .Lcva_v1_n_l1_k1
	v_readlane_b32 s48, v251, 6
	v_readlane_b32 s49, v251, 7
	s_mov_b32 s60, s54
	s_branch .Lcva_v1_n_l1_k3

; template <int NT> __device__ __forceinline__ void conv_tilesN(const Params& p, LAS unsigned char* lds, int tid, int t0, int stride, int t_end) {
;     ...
;         int mat, loc, ktn;
;         if (t < 7680) { mat = 0; loc = t; ktn = 32; }
;         else if (t < 9728) { mat = 1; loc = t - 7680; ktn = 64; }
;         else if (t < 10752) { mat = 2; loc = t - 9728; ktn = 32; }
;         else if (t < 16384) { mat = 3; loc = t - 10752; ktn = 32; }
;         else if (t < 19200) { mat = 4; loc = t - 16384; ktn = 88; }
;         else { mat = 5; loc = t - 19200; ktn = 32; }
;         const int n0 = (loc / ktn) * 64, k0 = (loc % ktn) * 64;
;         const int n = n0 + tx;
;         const float* ptr; int ld, col, kk0 = k0;
;         if (mat == 0) {
;           ptr = p.in[6]; ld = INW; col = n;
;           if (n >= OFF_RQ && n < OFF_RV) { const int s = n & 127; col = (n & ~127) + ((s >> 4) & 1) * 64 + (s >> 5) * 16 + (s & 15); }
;         } else if (mat == 1) {
;           ld = 2048; col = n;
;           if (k0 < 1024) { ptr = p.in[11]; } else if (k0 < 3072) { ptr = p.in[13]; kk0 = k0 - 1024; } else { ptr = p.in[16]; kk0 = k0 - 3072; }
;         } else if (mat == 2) { ptr = p.in[17]; ld = 2048; col = n; }
;         else if (mat == 3) {
;           const int T = n >> 8, s = n & 255;
;           const int f = 128 * T + 64 * (s >> 7) + 16 * ((s >> 5) & 3) + (s & 15);
;           ptr = ((s >> 4) & 1) ? p.in[21] : p.in[20]; ld = DFF; col = f;
;         } else if (mat == 4) { ptr = p.in[22]; ld = 2048; col = n; }
;         else { if (n < 1024) { ptr = p.in[14]; col = n; } else { ptr = p.in[15]; col = n - 1024; } ld = 1024; }
;         const float* s0 = ptr + (size_t)(kk0 + ty * 8) * ld + col;
; #pragma unroll
;         for (int r = 0; r < 8; ++r) v[q][r] = __builtin_nontemporal_load(s0 + (size_t)r * ld);
.Lcva_v1_n_l1_dd:
	global_load_dword v24, v[12:13], off nt
	v_lshl_add_u64 v[12:13], v[12:13], 0, s[52:53]
	global_load_dword v25, v[12:13], off nt
	v_lshl_add_u64 v[12:13], v[12:13], 0, s[52:53]
	global_load_dword v26, v[12:13], off nt
	v_lshl_add_u64 v[12:13], v[12:13], 0, s[52:53]
	global_load_dword v27, v[12:13], off nt
	v_lshl_add_u64 v[12:13], v[12:13], 0, s[52:53]
	global_load_dword v28, v[12:13], off nt
	v_lshl_add_u64 v[12:13], v[12:13], 0, s[52:53]
	global_load_dword v29, v[12:13], off nt
	v_lshl_add_u64 v[12:13], v[12:13], 0, s[52:53]
	global_load_dword v30, v[12:13], off nt
	v_lshl_add_u64 v[12:13], v[12:13], 0, s[52:53]
	global_load_dword v31, v[12:13], off nt
	s_add_i32 s47, s63, 2
	s_cmp_lt_u32 s47, 0x2600
	s_cbranch_scc0 .Lcva_v1_n_l2_m1
	s_sub_i32 s54, s47, 0x1e00
	s_lshr_b32 s55, s54, 6
	s_lshl_b32 s55, s55, 6
	s_and_b32 s54, s54, 63
	s_lshl_b32 s54, s54, 6
	s_mov_b32 s52, 0x2000
	s_cmpk_lt_u32 s54, 0x400
	s_cbranch_scc0 .Lcva_v1_n_l2_k1
	v_readlane_b32 s48, v251, 6
	v_readlane_b32 s49, v251, 7
	s_mov_b32 s60, s54
	s_branch .Lcva_v1_n_l2_k3

; template <int NT> __device__ __forceinline__ void conv_tilesN(const Params& p, LAS unsigned char* lds, int tid, int t0, int stride, int t_end) {
;     ...
;         int mat, loc, ktn;
;         if (t < 7680) { mat = 0; loc = t; ktn = 32; }
;         else if (t < 9728) { mat = 1; loc = t - 7680; ktn = 64; }
;         else if (t < 10752) { mat = 2; loc = t - 9728; ktn = 32; }
;         else if (t < 16384) { mat = 3; loc = t - 10752; ktn = 32; }
;         else if (t < 19200) { mat = 4; loc = t - 16384; ktn = 88; }
;         else { mat = 5; loc = t - 19200; ktn = 32; }
;         const int n0 = (loc / ktn) * 64, k0 = (loc % ktn) * 64;
;         const int n = n0 + tx;
;         const float* ptr; int ld, col, kk0 = k0;
;         if (mat == 0) {
;           ptr = p.in[6]; ld = INW; col = n;
;           if (n >= OFF_RQ && n < OFF_RV) { const int s = n & 127; col = (n & ~127) + ((s >> 4) & 1) * 64 + (s >> 5) * 16 + (s & 15); }
;         } else if (mat == 1) {
;           ld = 2048; col = n;
;           if (k0 < 1024) { ptr = p.in[11]; } else if (k0 < 3072) { ptr = p.in[13]; kk0 = k0 - 1024; } else { ptr = p.in[16]; kk0 = k0 - 3072; }
;         } else if (mat == 2) { ptr = p.in[17]; ld = 2048; col = n; }
;         else if (mat == 3) {
;           const int T = n >> 8, s = n & 255;
;           const int f = 128 * T + 64 * (s >> 7) + 16 * ((s >> 5) & 3) + (s & 15);
;           ptr = ((s >> 4) & 1) ? p.in[21] : p.in[20]; ld = DFF; col = f;
;         } else if (mat == 4) { ptr = p.in[22]; ld = 2048; col = n; }
;         else { if (n < 1024) { ptr = p.in[14]; col = n; } else { ptr = p.in[15]; col = n - 1024; } ld = 1024; }
;         const float* s0 = ptr + (size_t)(kk0 + ty * 8) * ld + col;
; #pragma unroll
;         for (int r = 0; r < 8; ++r) v[q][r] = __builtin_nontemporal_load(s0 + (size_t)r * ld);
.Lcva_v1_n_l2_dd:
	global_load_dword v32, v[12:13], off nt
	v_lshl_add_u64 v[12:13], v[12:13], 0, s[52:53]
	global_load_dword v33, v[12:13], off nt
	v_lshl_add_u64 v[12:13], v[12:13], 0, s[52:53]
	global_load_dword v34, v[12:13], off nt
	v_lshl_add_u64 v[12:13], v[12:13], 0, s[52:53]
	global_load_dword v35, v[12:13], off nt
	v_lshl_add_u64 v[12:13], v[12:13], 0, s[52:53]
	global_load_dword v36, v[12:13], off nt
	v_lshl_add_u64 v[12:13], v[12:13], 0, s[52:53]
	global_load_dword v37, v[12:13], off nt
	v_lshl_add_u64 v[12:13], v[12:13], 0, s[52:53]
	global_load_dword v38, v[12:13], off nt
	v_lshl_add_u64 v[12:13], v[12:13], 0, s[52:53]
	global_load_dword v39, v[12:13], off nt
	s_add_i32 s47, s63, 3
	s_cmp_lt_u32 s47, 0x2600
	s_cbranch_scc0 .Lcva_v1_n_l3_m1
	s_sub_i32 s54, s47, 0x1e00
	s_lshr_b32 s55, s54, 6
	s_lshl_b32 s55, s55, 6
	s_and_b32 s54, s54, 63
	s_lshl_b32 s54, s54, 6
	s_mov_b32 s52, 0x2000
	s_cmpk_lt_u32 s54, 0x400
	s_cbranch_scc0 .Lcva_v1_n_l3_k1
	v_readlane_b32 s48, v251, 6
	v_readlane_b32 s49, v251, 7
	s_mov_b32 s60, s54
	s_branch .Lcva_v1_n_l3_k3

; template <int NT> __device__ __forceinline__ void conv_tilesN(const Params& p, LAS unsigned char* lds, int tid, int t0, int stride, int t_end) {
;     ...
;         const float* s0 = ptr + (size_t)(kk0 + ty * 8) * ld + col;
; #pragma unroll
;         for (int r = 0; r < 8; ++r) v[q][r] = __builtin_nontemporal_load(s0 + (size_t)r * ld);
;       }
;     }
; #pragma unroll
;     for (int q = 0; q < NT; ++q) {
;       const int t = t0 + q * stride;
;       if (t < t_end) {
;         int loc, ktn, ldd; size_t dsto;
;         if (t < 7680) { loc = t; ktn = 32; ldd = 2048; dsto = WS_WIN; }
;         else if (t < 9728) { loc = t - 7680; ktn = 64; ldd = 4096; dsto = WS_WCAT; }
;         else if (t < 10752) { loc = t - 9728; ktn = 32; ldd = 2048; dsto = WS_WOUT; }
;         else if (t < 16384) { loc = t - 10752; ktn = 32; ldd = 2048; dsto = WS_WGU; }
;         else if (t < 19200) { loc = t - 16384; ktn = 88; ldd = 5632; dsto = WS_WDN; }
;         else { loc = t - 19200; ktn = 32; ldd = 2048; dsto = WS_WMKV; }
;         const int n0 = (loc / ktn) * 64, k0 = (loc % ktn) * 64;
.Lcva_v1_n_l3_dd:
	global_load_dword v40, v[12:13], off nt
	v_lshl_add_u64 v[12:13], v[12:13], 0, s[52:53]
	global_load_dword v41, v[12:13], off nt
	v_lshl_add_u64 v[12:13], v[12:13], 0, s[52:53]
	global_load_dword v42, v[12:13], off nt
	v_lshl_add_u64 v[12:13], v[12:13], 0, s[52:53]
	global_load_dword v43, v[12:13], off nt
	v_lshl_add_u64 v[12:13], v[12:13], 0, s[52:53]
	global_load_dword v44, v[12:13], off nt
	v_lshl_add_u64 v[12:13], v[12:13], 0, s[52:53]
	global_load_dword v45, v[12:13], off nt
	v_lshl_add_u64 v[12:13], v[12:13], 0, s[52:53]
	global_load_dword v46, v[12:13], off nt
	v_lshl_add_u64 v[12:13], v[12:13], 0, s[52:53]
	global_load_dword v47, v[12:13], off nt
	s_add_i32 s47, s46, 1
	s_cmp_lt_u32 s47, 0x2600
	s_cbranch_scc0 .Lcva_v1_a_s1_m1
	s_sub_i32 s54, s47, 0x1e00
	s_lshr_b32 s55, s54, 6
	s_lshl_b32 s55, s55, 6
	s_and_b32 s54, s54, 63
	s_lshl_b32 s54, s54, 6
	s_mov_b32 s58, 0x2000
	s_mul_i32 s60, s55, 0x2000
	s_lshl_b32 s61, s54, 1
	s_add_i32 s60, s60, s61
	s_add_u32 s56, s24, 0x6109000
	s_addc_u32 s57, s25, 0
	s_add_u32 s56, s56, s60
	s_addc_u32 s57, s57, 0
	v_mad_u32_u24 v14, v3, s58, v4
	s_branch .Lcva_v1_a_s1_dd

; __device__ __forceinline__ unsigned cvt_pk(float lo, float hi) { const f32x2 v = {lo, hi}; const bf16x2_t b = __builtin_convertvector(v, bf16x2_t); return __builtin_bit_cast(unsigned, b); }
; template <int NT> __device__ __forceinline__ void conv_tilesN(const Params& p, LAS unsigned char* lds, int tid, int t0, int stride, int t_end) {
;     ...
;         int loc, ktn, ldd; size_t dsto;
;         if (t < 7680) { loc = t; ktn = 32; ldd = 2048; dsto = WS_WIN; }
;         else if (t < 9728) { loc = t - 7680; ktn = 64; ldd = 4096; dsto = WS_WCAT; }
;         else if (t < 10752) { loc = t - 9728; ktn = 32; ldd = 2048; dsto = WS_WOUT; }
;         else if (t < 16384) { loc = t - 10752; ktn = 32; ldd = 2048; dsto = WS_WGU; }
;         else if (t < 19200) { loc = t - 16384; ktn = 88; ldd = 5632; dsto = WS_WDN; }
;         else { loc = t - 19200; ktn = 32; ldd = 2048; dsto = WS_WMKV; }
;         const int n0 = (loc / ktn) * 64, k0 = (loc % ktn) * 64;
;         __syncthreads();
; #pragma unroll
;         for (int r = 0; r < 8; ++r) tile[(ty * 8 + r) * 65 + tx] = v[q][r];
;         __syncthreads();
;         const int nn = tid >> 3, kc = (tid & 7) * 8;
;         float w[8];
; #pragma unroll
;         for (int e = 0; e < 8; ++e) w[e] = tile[(kc + e) * 65 + nn];
;         u32x4 o; o[0] = cvt_pk(w[0], w[1]); o[1] = cvt_pk(w[2], w[3]); o[2] = cvt_pk(w[4], w[5]); o[3] = cvt_pk(w[6], w[7]);
;         *(u32x4*)((bf16_t*)(ws + dsto) + (size_t)(n0 + nn) * ldd + k0 + kc) = o;
.Lcva_v1_a_s1_dd:
	s_barrier
	s_waitcnt vmcnt(48)
	ds_write_b32 v5, v76
	ds_write_b32 v5, v77 offset:260
	ds_write_b32 v5, v78 offset:520
	ds_write_b32 v5, v79 offset:780
	ds_write_b32 v5, v80 offset:1040
	ds_write_b32 v5, v81 offset:1300
	ds_write_b32 v5, v82 offset:1560
	ds_write_b32 v5, v83 offset:1820
	s_waitcnt lgkmcnt(0)
	s_barrier
	ds_read_b32 v48, v6
	ds_read_b32 v49, v6 offset:260
	ds_read_b32 v50, v6 offset:520
	ds_read_b32 v51, v6 offset:780
	ds_read_b32 v52, v6 offset:1040
	ds_read_b32 v53, v6 offset:1300
	ds_read_b32 v54, v6 offset:1560
	ds_read_b32 v55, v6 offset:1820
	s_waitcnt lgkmcnt(0)
	v_cvt_pk_bf16_f32 v56, v48, v49
	v_cvt_pk_bf16_f32 v57, v50, v51
	v_cvt_pk_bf16_f32 v58, v52, v53
	v_cvt_pk_bf16_f32 v59, v54, v55
	global_store_dwordx4 v14, v[56:59], s[56:57]
	s_add_i32 s47, s46, 2
	s_cmp_lt_u32 s47, 0x2600
	s_cbranch_scc0 .Lcva_v1_a_s2_m1
	s_sub_i32 s54, s47, 0x1e00
	s_lshr_b32 s55, s54, 6
	s_lshl_b32 s55, s55, 6
	s_and_b32 s54, s54, 63
	s_lshl_b32 s54, s54, 6
	s_mov_b32 s58, 0x2000
	s_mul_i32 s60, s55, 0x2000
	s_lshl_b32 s61, s54, 1
	s_add_i32 s60, s60, s61
	s_add_u32 s56, s24, 0x6109000
	s_addc_u32 s57, s25, 0
	s_add_u32 s56, s56, s60
	s_addc_u32 s57, s57, 0
	v_mad_u32_u24 v14, v3, s58, v4
	s_branch .Lcva_v1_a_s2_dd

; __device__ __forceinline__ unsigned cvt_pk(float lo, float hi) { const f32x2 v = {lo, hi}; const bf16x2_t b = __builtin_convertvector(v, bf16x2_t); return __builtin_bit_cast(unsigned, b); }
; template <int NT> __device__ __forceinline__ void conv_tilesN(const Params& p, LAS unsigned char* lds, int tid, int t0, int stride, int t_end) {
;     ...
;         int loc, ktn, ldd; size_t dsto;
;         if (t < 7680) { loc = t; ktn = 32; ldd = 2048; dsto = WS_WIN; }
;         else if (t < 9728) { loc = t - 7680; ktn = 64; ldd = 4096; dsto = WS_WCAT; }
;         else if (t < 10752) { loc = t - 9728; ktn = 32; ldd = 2048; dsto = WS_WOUT; }
;         else if (t < 16384) { loc = t - 10752; ktn = 32; ldd = 2048; dsto = WS_WGU; }
;         else if (t < 19200) { loc = t - 16384; ktn = 88; ldd = 5632; dsto = WS_WDN; }
;         else { loc = t - 19200; ktn = 32; ldd = 2048; dsto = WS_WMKV; }
;         const int n0 = (loc / ktn) * 64, k0 = (loc % ktn) * 64;
;         __syncthreads();
; #pragma unroll
;         for (int r = 0; r < 8; ++r) tile[(ty * 8 + r) * 65 + tx] = v[q][r];
;         __syncthreads();
;         const int nn = tid >> 3, kc = (tid & 7) * 8;
;         float w[8];
; #pragma unroll
;         for (int e = 0; e < 8; ++e) w[e] = tile[(kc + e) * 65 + nn];
;         u32x4 o; o[0] = cvt_pk(w[0], w[1]); o[1] = cvt_pk(w[2], w[3]); o[2] = cvt_pk(w[4], w[5]); o[3] = cvt_pk(w[6], w[7]);
;         *(u32x4*)((bf16_t*)(ws + dsto) + (size_t)(n0 + nn) * ldd + k0 + kc) = o;
.Lcva_v1_a_s2_dd:
	s_barrier
	s_waitcnt vmcnt(40)
	ds_write_b32 v5, v84
	ds_write_b32 v5, v85 offset:260
	ds_write_b32 v5, v86 offset:520
	ds_write_b32 v5, v87 offset:780
	ds_write_b32 v5, v88 offset:1040
	ds_write_b32 v5, v89 offset:1300
	ds_write_b32 v5, v90 offset:1560
	ds_write_b32 v5, v91 offset:1820
	s_waitcnt lgkmcnt(0)
	s_barrier
	ds_read_b32 v48, v6
	ds_read_b32 v49, v6 offset:260
	ds_read_b32 v50, v6 offset:520
	ds_read_b32 v51, v6 offset:780
	ds_read_b32 v52, v6 offset:1040
	ds_read_b32 v53, v6 offset:1300
	ds_read_b32 v54, v6 offset:1560
	ds_read_b32 v55, v6 offset:1820
	s_waitcnt lgkmcnt(0)
	v_cvt_pk_bf16_f32 v56, v48, v49
	v_cvt_pk_bf16_f32 v57, v50, v51
	v_cvt_pk_bf16_f32 v58, v52, v53
	v_cvt_pk_bf16_f32 v59, v54, v55
	global_store_dwordx4 v14, v[56:59], s[56:57]
	s_add_i32 s47, s46, 3
	s_cmp_lt_u32 s47, 0x2600
	s_cbranch_scc0 .Lcva_v1_a_s3_m1
	s_sub_i32 s54, s47, 0x1e00
	s_lshr_b32 s55, s54, 6
	s_lshl_b32 s55, s55, 6
	s_and_b32 s54, s54, 63
	s_lshl_b32 s54, s54, 6
	s_mov_b32 s58, 0x2000
	s_mul_i32 s60, s55, 0x2000
	s_lshl_b32 s61, s54, 1
	s_add_i32 s60, s60, s61
	s_add_u32 s56, s24, 0x6109000
	s_addc_u32 s57, s25, 0
	s_add_u32 s56, s56, s60
	s_addc_u32 s57, s57, 0
	v_mad_u32_u24 v14, v3, s58, v4
	s_branch .Lcva_v1_a_s3_dd

; __device__ __forceinline__ unsigned cvt_pk(float lo, float hi) { const f32x2 v = {lo, hi}; const bf16x2_t b = __builtin_convertvector(v, bf16x2_t); return __builtin_bit_cast(unsigned, b); }
; template <int NT> __device__ __forceinline__ void conv_tilesN(const Params& p, LAS unsigned char* lds, int tid, int t0, int stride, int t_end) {
;     ...
;         int loc, ktn, ldd; size_t dsto;
;         if (t < 7680) { loc = t; ktn = 32; ldd = 2048; dsto = WS_WIN; }
;         else if (t < 9728) { loc = t - 7680; ktn = 64; ldd = 4096; dsto = WS_WCAT; }
;         else if (t < 10752) { loc = t - 9728; ktn = 32; ldd = 2048; dsto = WS_WOUT; }
;         else if (t < 16384) { loc = t - 10752; ktn = 32; ldd = 2048; dsto = WS_WGU; }
;         else if (t < 19200) { loc = t - 16384; ktn = 88; ldd = 5632; dsto = WS_WDN; }
;         else { loc = t - 19200; ktn = 32; ldd = 2048; dsto = WS_WMKV; }
;         const int n0 = (loc / ktn) * 64, k0 = (loc % ktn) * 64;
;         __syncthreads();
; #pragma unroll
;         for (int r = 0; r < 8; ++r) tile[(ty * 8 + r) * 65 + tx] = v[q][r];
;         __syncthreads();
;         const int nn = tid >> 3, kc = (tid & 7) * 8;
;         float w[8];
; #pragma unroll
;         for (int e = 0; e < 8; ++e) w[e] = tile[(kc + e) * 65 + nn];
;         u32x4 o; o[0] = cvt_pk(w[0], w[1]); o[1] = cvt_pk(w[2], w[3]); o[2] = cvt_pk(w[4], w[5]); o[3] = cvt_pk(w[6], w[7]);
;         *(u32x4*)((bf16_t*)(ws + dsto) + (size_t)(n0 + nn) * ldd + k0 + kc) = o;
.Lcva_v1_b_s1_dd:
	s_barrier
	s_waitcnt vmcnt(16)
	ds_write_b32 v5, v76
	ds_write_b32 v5, v77 offset:260
	ds_write_b32 v5, v78 offset:520
	ds_write_b32 v5, v79 offset:780
	ds_write_b32 v5, v80 offset:1040
	ds_write_b32 v5, v81 offset:1300
	ds_write_b32 v5, v82 offset:1560
	ds_write_b32 v5, v83 offset:1820
	s_waitcnt lgkmcnt(0)
	s_barrier
	ds_read_b32 v48, v6
	ds_read_b32 v49, v6 offset:260
	ds_read_b32 v50, v6 offset:520
	ds_read_b32 v51, v6 offset:780
	ds_read_b32 v52, v6 offset:1040
	ds_read_b32 v53, v6 offset:1300
	ds_read_b32 v54, v6 offset:1560
	ds_read_b32 v55, v6 offset:1820
	s_waitcnt lgkmcnt(0)
	v_cvt_pk_bf16_f32 v56, v48, v49
	v_cvt_pk_bf16_f32 v57, v50, v51
	v_cvt_pk_bf16_f32 v58, v52, v53
	v_cvt_pk_bf16_f32 v59, v54, v55
	global_store_dwordx4 v14, v[56:59], s[56:57]
	s_add_i32 s47, s46, 2
	s_cmp_lt_u32 s47, 0x2600
	s_cbranch_scc0 .Lcva_v1_b_s2_m1
	s_sub_i32 s54, s47, 0x1e00
	s_lshr_b32 s55, s54, 6
	s_lshl_b32 s55, s55, 6
	s_and_b32 s54, s54, 63
	s_lshl_b32 s54, s54, 6
	s_mov_b32 s58, 0x2000
	s_mul_i32 s60, s55, 0x2000
	s_lshl_b32 s61, s54, 1
	s_add_i32 s60, s60, s61
	s_add_u32 s56, s24, 0x6109000
	s_addc_u32 s57, s25, 0
	s_add_u32 s56, s56, s60
	s_addc_u32 s57, s57, 0
	v_mad_u32_u24 v14, v3, s58, v4
	s_branch .Lcva_v1_b_s2_dd

; __device__ __forceinline__ unsigned cvt_pk(float lo, float hi) { const f32x2 v = {lo, hi}; const bf16x2_t b = __builtin_convertvector(v, bf16x2_t); return __builtin_bit_cast(unsigned, b); }
; template <int NT> __device__ __forceinline__ void conv_tilesN(const Params& p, LAS unsigned char* lds, int tid, int t0, int stride, int t_end) {
;     ...
;         int loc, ktn, ldd; size_t dsto;
;         if (t < 7680) { loc = t; ktn = 32; ldd = 2048; dsto = WS_WIN; }
;         else if (t < 9728) { loc = t - 7680; ktn = 64; ldd = 4096; dsto = WS_WCAT; }
;         else if (t < 10752) { loc = t - 9728; ktn = 32; ldd = 2048; dsto = WS_WOUT; }
;         else if (t < 16384) { loc = t - 10752; ktn = 32; ldd = 2048; dsto = WS_WGU; }
;         else if (t < 19200) { loc = t - 16384; ktn = 88; ldd = 5632; dsto = WS_WDN; }
;         else { loc = t - 19200; ktn = 32; ldd = 2048; dsto = WS_WMKV; }
;         const int n0 = (loc / ktn) * 64, k0 = (loc % ktn) * 64;
;         __syncthreads();
; #pragma unroll
;         for (int r = 0; r < 8; ++r) tile[(ty * 8 + r) * 65 + tx] = v[q][r];
;         __syncthreads();
;         const int nn = tid >> 3, kc = (tid & 7) * 8;
;         float w[8];
; #pragma unroll
;         for (int e = 0; e < 8; ++e) w[e] = tile[(kc + e) * 65 + nn];
;         u32x4 o; o[0] = cvt_pk(w[0], w[1]); o[1] = cvt_pk(w[2], w[3]); o[2] = cvt_pk(w[4], w[5]); o[3] = cvt_pk(w[6], w[7]);
;         *(u32x4*)((bf16_t*)(ws + dsto) + (size_t)(n0 + nn) * ldd + k0 + kc) = o;
.Lcva_v1_b_s2_dd:
	s_barrier
	s_waitcnt vmcnt(8)
	ds_write_b32 v5, v84
	ds_write_b32 v5, v85 offset:260
	ds_write_b32 v5, v86 offset:520
	ds_write_b32 v5, v87 offset:780
	ds_write_b32 v5, v88 offset:1040
	ds_write_b32 v5, v89 offset:1300
	ds_write_b32 v5, v90 offset:1560
	ds_write_b32 v5, v91 offset:1820
	s_waitcnt lgkmcnt(0)
	s_barrier
	ds_read_b32 v48, v6
	ds_read_b32 v49, v6 offset:260
	ds_read_b32 v50, v6 offset:520
	ds_read_b32 v51, v6 offset:780
	ds_read_b32 v52, v6 offset:1040
	ds_read_b32 v53, v6 offset:1300
	ds_read_b32 v54, v6 offset:1560
	ds_read_b32 v55, v6 offset:1820
	s_waitcnt lgkmcnt(0)
	v_cvt_pk_bf16_f32 v56, v48, v49
	v_cvt_pk_bf16_f32 v57, v50, v51
	v_cvt_pk_bf16_f32 v58, v52, v53
	v_cvt_pk_bf16_f32 v59, v54, v55
	global_store_dwordx4 v14, v[56:59], s[56:57]
	s_add_i32 s47, s46, 3
	s_cmp_lt_u32 s47, 0x2600
	s_cbranch_scc0 .Lcva_v1_b_s3_m1
	s_sub_i32 s54, s47, 0x1e00
	s_lshr_b32 s55, s54, 6
	s_lshl_b32 s55, s55, 6
	s_and_b32 s54, s54, 63
	s_lshl_b32 s54, s54, 6
	s_mov_b32 s58, 0x2000
	s_mul_i32 s60, s55, 0x2000
	s_lshl_b32 s61, s54, 1
	s_add_i32 s60, s60, s61
	s_add_u32 s56, s24, 0x6109000
	s_addc_u32 s57, s25, 0
	s_add_u32 s56, s56, s60
	s_addc_u32 s57, s57, 0
	v_mad_u32_u24 v14, v3, s58, v4
	s_branch .Lcva_v1_b_s3_dd

; #define LAS __attribute__((address_space(3)))
; __device__ __forceinline__ void conv_queue(const Params& p, LAS unsigned char* lds, unsigned* ctr, int t_begin, int t_end) {
;   int tid = threadIdx.x; asm volatile("" : "+v"(tid));
;   LAS unsigned* slot = (LAS unsigned*)(lds + LDS_CTL);
;   unsigned nxt = 0u;
;   if (tid == 0) nxt = atomicAdd(ctr, 4u);
;     ...
;   }
; }
.Lcva_done:
	s_waitcnt vmcnt(0) lgkmcnt(0)
	s_branch .LBB0_994
	v_mov_b32_e32 v0, v226
	v_mov_b32_e32 v11, 0
	v_cmp_eq_u32_e64 s[36:37], 0, v0
	s_and_saveexec_b64 s[38:39], s[36:37]
	s_cbranch_execz .LBB0_1214
	s_mov_b64 s[44:45], exec
	v_mbcnt_lo_u32_b32 v1, s44, 0
	v_mbcnt_hi_u32_b32 v1, s45, v1
	v_cmp_eq_u32_e32 vcc, 0, v1
	s_and_saveexec_b64 s[40:41], vcc
	s_cbranch_execz .LBB0_1213
	s_bcnt1_i32_b64 s29, s[44:45]
	s_lshl_b32 s29, s29, 2
	v_mov_b32_e32 v2, s29
	global_atomic_add v2, v65, v2, s[24:25] offset:16 sc0
